# phase 2 writes r/k/v with the default cache policy (other phase-2 outputs stay nt): the scan and the LoRA epilogue re-read them soon after
# speedup vs baseline: 1.0084x; 1.0021x over previous
; __device__ __forceinline__ void unpack8(const u32x4 w, float (&f)[8]) { f[0] = bflo(w.x); f[1] = bfhi(w.x); f[2] = bflo(w.y); f[3] = bfhi(w.y); f[4] = bflo(w.z); f[5] = bfhi(w.z); f[6] = bflo(w.w); f[7] = bfhi(w.w); }
; __device__ __forceinline__ u32x4 pack8(const float (&f)[8]) { u32x4 o; o.x = pk2(f[0], f[1]); o.y = pk2(f[2], f[3]); o.z = pk2(f[4], f[5]); o.w = pk2(f[6], f[7]); return o; }
; __device__ __forceinline__ float sigmoidf_(float x) { return __builtin_amdgcn_rcpf(1.0f + __expf(-x)); }
; __device__ __forceinline__ float tanhf_(float x) { return 1.0f - 2.0f * __builtin_amdgcn_rcpf(__expf(2.0f * x) + 1.0f); }
; template <int CH> __device__ __forceinline__ void p2_rwkv_chunk(const Params& p, int t0, int lane) {
;     ...
;     for (int i = 0; i < 16; ++i) {
;         const int t = t0 + i; const bool hasn = (t & (T_SEQ - 1)) != T_SEQ - 1;
;         if (hasn) unpack8(raw, N); else {
; #pragma unroll
;             for (int q = 0; q < 8; ++q) N[q] = 0.f; }
;         if (i < 15 && ((t + 1) & (T_SEQ - 1)) != T_SEQ - 1) raw = __builtin_nontemporal_load((const u32x4*)(zc + (size_t)(i + 2) * ZLD));
;         float zs[8];
; #pragma unroll
;         for (int q = 0; q < 8; ++q) zs[q] = C[q] + mu[q] * (0.5f * (P[q] + N[q]) - C[q]);
;         if (CH < 3) {
;             *(u32x4*)(RKV + (size_t)t * 1536 + c) = pack8(zs);
;             if (CH == 1) { float s2 = 0.f;
; #pragma unroll
;                 for (int q = 0; q < 8; ++q) { const float v = zs[q] * kq[q]; s2 += v * v; }
;                 s2 = red8s(s2);
;                 if ((lane & 7) == 0) RINV[t * 8 + (lane >> 3)] = rsqrtf(fmaxf(s2, 1e-24f)); }
;         } else {
;             const int cc = c - 1536; float o[8];
; #pragma unroll
;             for (int q = 0; q < 8; ++q) o[q] = cc < 128 ? tanhf_(zs[q]) : (cc < 192 ? zs[q] : sigmoidf_(zs[q]));
;             *(u32x4*)(AP + (size_t)t * KLORA + cc) = pack8(o);
;         }
; #pragma unroll
;         for (int q = 0; q < 8; ++q) { P[q] = C[q]; C[q] = N[q]; }
.Lp2_nz_3:
	v_lshlrev_b32_e32 v80, 16, v8
	v_and_b32_e32 v81, 0xffff0000, v8
	v_lshlrev_b32_e32 v82, 16, v9
	v_and_b32_e32 v83, 0xffff0000, v9
	v_lshlrev_b32_e32 v84, 16, v10
	v_and_b32_e32 v85, 0xffff0000, v10
	v_lshlrev_b32_e32 v86, 16, v11
	v_and_b32_e32 v87, 0xffff0000, v11
	v_lshlrev_b32_e32 v88, 16, v12
	v_and_b32_e32 v89, 0xffff0000, v12
	v_lshlrev_b32_e32 v90, 16, v13
	v_and_b32_e32 v91, 0xffff0000, v13
	v_lshlrev_b32_e32 v92, 16, v14
	v_and_b32_e32 v93, 0xffff0000, v14
	v_lshlrev_b32_e32 v94, 16, v15
	v_and_b32_e32 v95, 0xffff0000, v15
	v_lshlrev_b32_e32 v96, 16, v16
	v_and_b32_e32 v97, 0xffff0000, v16
	v_lshlrev_b32_e32 v98, 16, v17
	v_and_b32_e32 v99, 0xffff0000, v17
	v_lshlrev_b32_e32 v100, 16, v18
	v_and_b32_e32 v101, 0xffff0000, v18
	v_lshlrev_b32_e32 v102, 16, v19
	v_and_b32_e32 v103, 0xffff0000, v19
	v_add_f32_e32 v136, v80, v96
	v_add_f32_e32 v137, v81, v97
	v_add_f32_e32 v138, v82, v98
	v_add_f32_e32 v139, v83, v99
	v_add_f32_e32 v140, v84, v100
	v_add_f32_e32 v141, v85, v101
	v_add_f32_e32 v142, v86, v102
	v_add_f32_e32 v143, v87, v103
	v_fma_f32 v136, v136, 0.5, -v88
	v_fma_f32 v137, v137, 0.5, -v89
	v_fma_f32 v138, v138, 0.5, -v90
	v_fma_f32 v139, v139, 0.5, -v91
	v_fma_f32 v140, v140, 0.5, -v92
	v_fma_f32 v141, v141, 0.5, -v93
	v_fma_f32 v142, v142, 0.5, -v94
	v_fma_f32 v143, v143, 0.5, -v95
	v_fma_f32 v128, v104, v136, v88
	v_fma_f32 v129, v105, v137, v89
	v_fma_f32 v130, v106, v138, v90
	v_fma_f32 v131, v107, v139, v91
	v_fma_f32 v132, v108, v140, v92
	v_fma_f32 v133, v109, v141, v93
	v_fma_f32 v134, v110, v142, v94
	v_fma_f32 v135, v111, v143, v95
	v_cvt_pk_bf16_f32 v246, v128, v129
	v_cvt_pk_bf16_f32 v247, v130, v131
	v_cvt_pk_bf16_f32 v248, v132, v133
	v_cvt_pk_bf16_f32 v249, v134, v135
	global_store_dwordx4 v5, v[246:249], s[58:59]
	v_add_u32_e32 v5, 0xc00, v5
	v_lshlrev_b32_e32 v80, 16, v20
	v_and_b32_e32 v81, 0xffff0000, v20
	v_lshlrev_b32_e32 v82, 16, v21
	v_and_b32_e32 v83, 0xffff0000, v21
	v_lshlrev_b32_e32 v84, 16, v22
	v_and_b32_e32 v85, 0xffff0000, v22
	v_lshlrev_b32_e32 v86, 16, v23
	v_and_b32_e32 v87, 0xffff0000, v23
	v_add_f32_e32 v136, v88, v80
	v_add_f32_e32 v137, v89, v81
	v_add_f32_e32 v138, v90, v82
	v_add_f32_e32 v139, v91, v83
	v_add_f32_e32 v140, v92, v84
	v_add_f32_e32 v141, v93, v85
	v_add_f32_e32 v142, v94, v86
	v_add_f32_e32 v143, v95, v87
	v_fma_f32 v136, v136, 0.5, -v96
	v_fma_f32 v137, v137, 0.5, -v97
	v_fma_f32 v138, v138, 0.5, -v98
	v_fma_f32 v139, v139, 0.5, -v99
	v_fma_f32 v140, v140, 0.5, -v100
	v_fma_f32 v141, v141, 0.5, -v101
	v_fma_f32 v142, v142, 0.5, -v102
	v_fma_f32 v143, v143, 0.5, -v103
	v_fma_f32 v128, v104, v136, v96
	v_fma_f32 v129, v105, v137, v97
	v_fma_f32 v130, v106, v138, v98
	v_fma_f32 v131, v107, v139, v99
	v_fma_f32 v132, v108, v140, v100
	v_fma_f32 v133, v109, v141, v101
	v_fma_f32 v134, v110, v142, v102
	v_fma_f32 v135, v111, v143, v103
	v_cvt_pk_bf16_f32 v246, v128, v129
	v_cvt_pk_bf16_f32 v247, v130, v131
	v_cvt_pk_bf16_f32 v248, v132, v133
	v_cvt_pk_bf16_f32 v249, v134, v135
	global_store_dwordx4 v5, v[246:249], s[58:59]
	v_add_u32_e32 v5, 0xc00, v5
	v_lshlrev_b32_e32 v88, 16, v24
	v_and_b32_e32 v89, 0xffff0000, v24
	v_lshlrev_b32_e32 v90, 16, v25
	v_and_b32_e32 v91, 0xffff0000, v25
	v_lshlrev_b32_e32 v92, 16, v26
	v_and_b32_e32 v93, 0xffff0000, v26
	v_lshlrev_b32_e32 v94, 16, v27
	v_and_b32_e32 v95, 0xffff0000, v27
	v_add_f32_e32 v136, v96, v88
	v_add_f32_e32 v137, v97, v89
	v_add_f32_e32 v138, v98, v90
	v_add_f32_e32 v139, v99, v91
	v_add_f32_e32 v140, v100, v92
	v_add_f32_e32 v141, v101, v93
	v_add_f32_e32 v142, v102, v94
	v_add_f32_e32 v143, v103, v95
	v_fma_f32 v136, v136, 0.5, -v80
	v_fma_f32 v137, v137, 0.5, -v81
	v_fma_f32 v138, v138, 0.5, -v82
	v_fma_f32 v139, v139, 0.5, -v83
	v_fma_f32 v140, v140, 0.5, -v84
	v_fma_f32 v141, v141, 0.5, -v85
	v_fma_f32 v142, v142, 0.5, -v86
	v_fma_f32 v143, v143, 0.5, -v87
	v_fma_f32 v128, v104, v136, v80
	v_fma_f32 v129, v105, v137, v81
	v_fma_f32 v130, v106, v138, v82
	v_fma_f32 v131, v107, v139, v83
	v_fma_f32 v132, v108, v140, v84
	v_fma_f32 v133, v109, v141, v85
	v_fma_f32 v134, v110, v142, v86
	v_fma_f32 v135, v111, v143, v87
	v_cvt_pk_bf16_f32 v246, v128, v129
	v_cvt_pk_bf16_f32 v247, v130, v131
	v_cvt_pk_bf16_f32 v248, v132, v133
	v_cvt_pk_bf16_f32 v249, v134, v135
	global_store_dwordx4 v5, v[246:249], s[58:59]
	v_add_u32_e32 v5, 0xc00, v5
	v_lshlrev_b32_e32 v96, 16, v28
	v_and_b32_e32 v97, 0xffff0000, v28
	v_lshlrev_b32_e32 v98, 16, v29
	v_and_b32_e32 v99, 0xffff0000, v29
	v_lshlrev_b32_e32 v100, 16, v30
	v_and_b32_e32 v101, 0xffff0000, v30
	v_lshlrev_b32_e32 v102, 16, v31
	v_and_b32_e32 v103, 0xffff0000, v31
	v_add_f32_e32 v136, v80, v96
	v_add_f32_e32 v137, v81, v97
	v_add_f32_e32 v138, v82, v98
	v_add_f32_e32 v139, v83, v99
	v_add_f32_e32 v140, v84, v100
	v_add_f32_e32 v141, v85, v101
	v_add_f32_e32 v142, v86, v102
	v_add_f32_e32 v143, v87, v103
	v_fma_f32 v136, v136, 0.5, -v88
	v_fma_f32 v137, v137, 0.5, -v89
	v_fma_f32 v138, v138, 0.5, -v90
	v_fma_f32 v139, v139, 0.5, -v91
	v_fma_f32 v140, v140, 0.5, -v92
	v_fma_f32 v141, v141, 0.5, -v93
	v_fma_f32 v142, v142, 0.5, -v94
	v_fma_f32 v143, v143, 0.5, -v95
	v_fma_f32 v128, v104, v136, v88
	v_fma_f32 v129, v105, v137, v89
	v_fma_f32 v130, v106, v138, v90
	v_fma_f32 v131, v107, v139, v91
	v_fma_f32 v132, v108, v140, v92
	v_fma_f32 v133, v109, v141, v93
	v_fma_f32 v134, v110, v142, v94
	v_fma_f32 v135, v111, v143, v95
	v_cvt_pk_bf16_f32 v246, v128, v129
	v_cvt_pk_bf16_f32 v247, v130, v131
	v_cvt_pk_bf16_f32 v248, v132, v133
	v_cvt_pk_bf16_f32 v249, v134, v135
	global_store_dwordx4 v5, v[246:249], s[58:59]
	v_add_u32_e32 v5, 0xc00, v5
	v_lshlrev_b32_e32 v80, 16, v32
; __device__ __forceinline__ void unpack8(const u32x4 w, float (&f)[8]) { f[0] = bflo(w.x); f[1] = bfhi(w.x); f[2] = bflo(w.y); f[3] = bfhi(w.y); f[4] = bflo(w.z); f[5] = bfhi(w.z); f[6] = bflo(w.w); f[7] = bfhi(w.w); }
; __device__ __forceinline__ u32x4 pack8(const float (&f)[8]) { u32x4 o; o.x = pk2(f[0], f[1]); o.y = pk2(f[2], f[3]); o.z = pk2(f[4], f[5]); o.w = pk2(f[6], f[7]); return o; }
; __device__ __forceinline__ float sigmoidf_(float x) { return __builtin_amdgcn_rcpf(1.0f + __expf(-x)); }
; __device__ __forceinline__ float tanhf_(float x) { return 1.0f - 2.0f * __builtin_amdgcn_rcpf(__expf(2.0f * x) + 1.0f); }
; template <int CH> __device__ __forceinline__ void p2_rwkv_chunk(const Params& p, int t0, int lane) {
;     ...
;     for (int i = 0; i < 16; ++i) {
;         const int t = t0 + i; const bool hasn = (t & (T_SEQ - 1)) != T_SEQ - 1;
;         if (hasn) unpack8(raw, N); else {
; #pragma unroll
;             for (int q = 0; q < 8; ++q) N[q] = 0.f; }
;         if (i < 15 && ((t + 1) & (T_SEQ - 1)) != T_SEQ - 1) raw = __builtin_nontemporal_load((const u32x4*)(zc + (size_t)(i + 2) * ZLD));
;         float zs[8];
; #pragma unroll
;         for (int q = 0; q < 8; ++q) zs[q] = C[q] + mu[q] * (0.5f * (P[q] + N[q]) - C[q]);
;         if (CH < 3) {
;             *(u32x4*)(RKV + (size_t)t * 1536 + c) = pack8(zs);
;             if (CH == 1) { float s2 = 0.f;
; #pragma unroll
;                 for (int q = 0; q < 8; ++q) { const float v = zs[q] * kq[q]; s2 += v * v; }
;                 s2 = red8s(s2);
;                 if ((lane & 7) == 0) RINV[t * 8 + (lane >> 3)] = rsqrtf(fmaxf(s2, 1e-24f)); }
;         } else {
;             const int cc = c - 1536; float o[8];
; #pragma unroll
;             for (int q = 0; q < 8; ++q) o[q] = cc < 128 ? tanhf_(zs[q]) : (cc < 192 ? zs[q] : sigmoidf_(zs[q]));
;             *(u32x4*)(AP + (size_t)t * KLORA + cc) = pack8(o);
;         }
; #pragma unroll
;         for (int q = 0; q < 8; ++q) { P[q] = C[q]; C[q] = N[q]; }
	v_and_b32_e32 v81, 0xffff0000, v32
	v_lshlrev_b32_e32 v82, 16, v33
	v_and_b32_e32 v83, 0xffff0000, v33
	v_lshlrev_b32_e32 v84, 16, v34
	v_and_b32_e32 v85, 0xffff0000, v34
	v_lshlrev_b32_e32 v86, 16, v35
	v_and_b32_e32 v87, 0xffff0000, v35
	v_add_f32_e32 v136, v88, v80
	v_add_f32_e32 v137, v89, v81
	v_add_f32_e32 v138, v90, v82
	v_add_f32_e32 v139, v91, v83
	v_add_f32_e32 v140, v92, v84
	v_add_f32_e32 v141, v93, v85
	v_add_f32_e32 v142, v94, v86
	v_add_f32_e32 v143, v95, v87
	v_fma_f32 v136, v136, 0.5, -v96
	v_fma_f32 v137, v137, 0.5, -v97
	v_fma_f32 v138, v138, 0.5, -v98
	v_fma_f32 v139, v139, 0.5, -v99
	v_fma_f32 v140, v140, 0.5, -v100
	v_fma_f32 v141, v141, 0.5, -v101
	v_fma_f32 v142, v142, 0.5, -v102
	v_fma_f32 v143, v143, 0.5, -v103
	v_fma_f32 v128, v104, v136, v96
	v_fma_f32 v129, v105, v137, v97
	v_fma_f32 v130, v106, v138, v98
	v_fma_f32 v131, v107, v139, v99
	v_fma_f32 v132, v108, v140, v100
	v_fma_f32 v133, v109, v141, v101
	v_fma_f32 v134, v110, v142, v102
	v_fma_f32 v135, v111, v143, v103
	v_cvt_pk_bf16_f32 v246, v128, v129
	v_cvt_pk_bf16_f32 v247, v130, v131
	v_cvt_pk_bf16_f32 v248, v132, v133
	v_cvt_pk_bf16_f32 v249, v134, v135
	global_store_dwordx4 v5, v[246:249], s[58:59]
	v_add_u32_e32 v5, 0xc00, v5
	v_lshlrev_b32_e32 v88, 16, v36
	v_and_b32_e32 v89, 0xffff0000, v36
	v_lshlrev_b32_e32 v90, 16, v37
	v_and_b32_e32 v91, 0xffff0000, v37
	v_lshlrev_b32_e32 v92, 16, v38
	v_and_b32_e32 v93, 0xffff0000, v38
	v_lshlrev_b32_e32 v94, 16, v39
	v_and_b32_e32 v95, 0xffff0000, v39
	v_add_f32_e32 v136, v96, v88
	v_add_f32_e32 v137, v97, v89
	v_add_f32_e32 v138, v98, v90
	v_add_f32_e32 v139, v99, v91
	v_add_f32_e32 v140, v100, v92
	v_add_f32_e32 v141, v101, v93
	v_add_f32_e32 v142, v102, v94
	v_add_f32_e32 v143, v103, v95
	v_fma_f32 v136, v136, 0.5, -v80
	v_fma_f32 v137, v137, 0.5, -v81
	v_fma_f32 v138, v138, 0.5, -v82
	v_fma_f32 v139, v139, 0.5, -v83
	v_fma_f32 v140, v140, 0.5, -v84
	v_fma_f32 v141, v141, 0.5, -v85
	v_fma_f32 v142, v142, 0.5, -v86
	v_fma_f32 v143, v143, 0.5, -v87
	v_fma_f32 v128, v104, v136, v80
	v_fma_f32 v129, v105, v137, v81
	v_fma_f32 v130, v106, v138, v82
	v_fma_f32 v131, v107, v139, v83
	v_fma_f32 v132, v108, v140, v84
	v_fma_f32 v133, v109, v141, v85
	v_fma_f32 v134, v110, v142, v86
	v_fma_f32 v135, v111, v143, v87
	v_cvt_pk_bf16_f32 v246, v128, v129
	v_cvt_pk_bf16_f32 v247, v130, v131
	v_cvt_pk_bf16_f32 v248, v132, v133
	v_cvt_pk_bf16_f32 v249, v134, v135
	global_store_dwordx4 v5, v[246:249], s[58:59]
	v_add_u32_e32 v5, 0xc00, v5
	v_lshlrev_b32_e32 v96, 16, v40
	v_and_b32_e32 v97, 0xffff0000, v40
	v_lshlrev_b32_e32 v98, 16, v41
	v_and_b32_e32 v99, 0xffff0000, v41
	v_lshlrev_b32_e32 v100, 16, v42
	v_and_b32_e32 v101, 0xffff0000, v42
	v_lshlrev_b32_e32 v102, 16, v43
	v_and_b32_e32 v103, 0xffff0000, v43
	v_add_f32_e32 v136, v80, v96
	v_add_f32_e32 v137, v81, v97
	v_add_f32_e32 v138, v82, v98
	v_add_f32_e32 v139, v83, v99
	v_add_f32_e32 v140, v84, v100
	v_add_f32_e32 v141, v85, v101
	v_add_f32_e32 v142, v86, v102
	v_add_f32_e32 v143, v87, v103
	v_fma_f32 v136, v136, 0.5, -v88
	v_fma_f32 v137, v137, 0.5, -v89
	v_fma_f32 v138, v138, 0.5, -v90
	v_fma_f32 v139, v139, 0.5, -v91
	v_fma_f32 v140, v140, 0.5, -v92
	v_fma_f32 v141, v141, 0.5, -v93
	v_fma_f32 v142, v142, 0.5, -v94
	v_fma_f32 v143, v143, 0.5, -v95
	v_fma_f32 v128, v104, v136, v88
	v_fma_f32 v129, v105, v137, v89
	v_fma_f32 v130, v106, v138, v90
	v_fma_f32 v131, v107, v139, v91
	v_fma_f32 v132, v108, v140, v92
	v_fma_f32 v133, v109, v141, v93
	v_fma_f32 v134, v110, v142, v94
	v_fma_f32 v135, v111, v143, v95
	v_cvt_pk_bf16_f32 v246, v128, v129
	v_cvt_pk_bf16_f32 v247, v130, v131
	v_cvt_pk_bf16_f32 v248, v132, v133
	v_cvt_pk_bf16_f32 v249, v134, v135
	global_store_dwordx4 v5, v[246:249], s[58:59]
	v_add_u32_e32 v5, 0xc00, v5
	v_lshlrev_b32_e32 v80, 16, v44
	v_and_b32_e32 v81, 0xffff0000, v44
	v_lshlrev_b32_e32 v82, 16, v45
	v_and_b32_e32 v83, 0xffff0000, v45
	v_lshlrev_b32_e32 v84, 16, v46
	v_and_b32_e32 v85, 0xffff0000, v46
	v_lshlrev_b32_e32 v86, 16, v47
	v_and_b32_e32 v87, 0xffff0000, v47
	v_add_f32_e32 v136, v88, v80
	v_add_f32_e32 v137, v89, v81
	v_add_f32_e32 v138, v90, v82
	v_add_f32_e32 v139, v91, v83
	v_add_f32_e32 v140, v92, v84
	v_add_f32_e32 v141, v93, v85
	v_add_f32_e32 v142, v94, v86
	v_add_f32_e32 v143, v95, v87
	v_fma_f32 v136, v136, 0.5, -v96
	v_fma_f32 v137, v137, 0.5, -v97
	v_fma_f32 v138, v138, 0.5, -v98
	v_fma_f32 v139, v139, 0.5, -v99
	v_fma_f32 v140, v140, 0.5, -v100
	v_fma_f32 v141, v141, 0.5, -v101
	v_fma_f32 v142, v142, 0.5, -v102
	v_fma_f32 v143, v143, 0.5, -v103
	v_fma_f32 v128, v104, v136, v96
	v_fma_f32 v129, v105, v137, v97
	v_fma_f32 v130, v106, v138, v98
	v_fma_f32 v131, v107, v139, v99
	v_fma_f32 v132, v108, v140, v100
	v_fma_f32 v133, v109, v141, v101
	v_fma_f32 v134, v110, v142, v102
	v_fma_f32 v135, v111, v143, v103
	v_cvt_pk_bf16_f32 v246, v128, v129
	v_cvt_pk_bf16_f32 v247, v130, v131
	v_cvt_pk_bf16_f32 v248, v132, v133
	v_cvt_pk_bf16_f32 v249, v134, v135
	global_store_dwordx4 v5, v[246:249], s[58:59]
	v_add_u32_e32 v5, 0xc00, v5
	v_lshlrev_b32_e32 v88, 16, v48
	v_and_b32_e32 v89, 0xffff0000, v48
	v_lshlrev_b32_e32 v90, 16, v49
	v_and_b32_e32 v91, 0xffff0000, v49
	v_lshlrev_b32_e32 v92, 16, v50
	v_and_b32_e32 v93, 0xffff0000, v50
	v_lshlrev_b32_e32 v94, 16, v51
	v_and_b32_e32 v95, 0xffff0000, v51
	v_add_f32_e32 v136, v96, v88
	v_add_f32_e32 v137, v97, v89
	v_add_f32_e32 v138, v98, v90
	v_add_f32_e32 v139, v99, v91
	v_add_f32_e32 v140, v100, v92
	v_add_f32_e32 v141, v101, v93
	v_add_f32_e32 v142, v102, v94
	v_add_f32_e32 v143, v103, v95
	v_fma_f32 v136, v136, 0.5, -v80
	v_fma_f32 v137, v137, 0.5, -v81
	v_fma_f32 v138, v138, 0.5, -v82
; __device__ __forceinline__ void unpack8(const u32x4 w, float (&f)[8]) { f[0] = bflo(w.x); f[1] = bfhi(w.x); f[2] = bflo(w.y); f[3] = bfhi(w.y); f[4] = bflo(w.z); f[5] = bfhi(w.z); f[6] = bflo(w.w); f[7] = bfhi(w.w); }
; __device__ __forceinline__ u32x4 pack8(const float (&f)[8]) { u32x4 o; o.x = pk2(f[0], f[1]); o.y = pk2(f[2], f[3]); o.z = pk2(f[4], f[5]); o.w = pk2(f[6], f[7]); return o; }
; __device__ __forceinline__ float sigmoidf_(float x) { return __builtin_amdgcn_rcpf(1.0f + __expf(-x)); }
; __device__ __forceinline__ float tanhf_(float x) { return 1.0f - 2.0f * __builtin_amdgcn_rcpf(__expf(2.0f * x) + 1.0f); }
; template <int CH> __device__ __forceinline__ void p2_rwkv_chunk(const Params& p, int t0, int lane) {
;     ...
;     for (int i = 0; i < 16; ++i) {
;         const int t = t0 + i; const bool hasn = (t & (T_SEQ - 1)) != T_SEQ - 1;
;         if (hasn) unpack8(raw, N); else {
; #pragma unroll
;             for (int q = 0; q < 8; ++q) N[q] = 0.f; }
;         if (i < 15 && ((t + 1) & (T_SEQ - 1)) != T_SEQ - 1) raw = __builtin_nontemporal_load((const u32x4*)(zc + (size_t)(i + 2) * ZLD));
;         float zs[8];
; #pragma unroll
;         for (int q = 0; q < 8; ++q) zs[q] = C[q] + mu[q] * (0.5f * (P[q] + N[q]) - C[q]);
;         if (CH < 3) {
;             *(u32x4*)(RKV + (size_t)t * 1536 + c) = pack8(zs);
;             if (CH == 1) { float s2 = 0.f;
; #pragma unroll
;                 for (int q = 0; q < 8; ++q) { const float v = zs[q] * kq[q]; s2 += v * v; }
;                 s2 = red8s(s2);
;                 if ((lane & 7) == 0) RINV[t * 8 + (lane >> 3)] = rsqrtf(fmaxf(s2, 1e-24f)); }
;         } else {
;             const int cc = c - 1536; float o[8];
; #pragma unroll
;             for (int q = 0; q < 8; ++q) o[q] = cc < 128 ? tanhf_(zs[q]) : (cc < 192 ? zs[q] : sigmoidf_(zs[q]));
;             *(u32x4*)(AP + (size_t)t * KLORA + cc) = pack8(o);
;         }
; #pragma unroll
;         for (int q = 0; q < 8; ++q) { P[q] = C[q]; C[q] = N[q]; }
	v_fma_f32 v139, v139, 0.5, -v83
	v_fma_f32 v140, v140, 0.5, -v84
	v_fma_f32 v141, v141, 0.5, -v85
	v_fma_f32 v142, v142, 0.5, -v86
	v_fma_f32 v143, v143, 0.5, -v87
	v_fma_f32 v128, v104, v136, v80
	v_fma_f32 v129, v105, v137, v81
	v_fma_f32 v130, v106, v138, v82
	v_fma_f32 v131, v107, v139, v83
	v_fma_f32 v132, v108, v140, v84
	v_fma_f32 v133, v109, v141, v85
	v_fma_f32 v134, v110, v142, v86
	v_fma_f32 v135, v111, v143, v87
	v_cvt_pk_bf16_f32 v246, v128, v129
	v_cvt_pk_bf16_f32 v247, v130, v131
	v_cvt_pk_bf16_f32 v248, v132, v133
	v_cvt_pk_bf16_f32 v249, v134, v135
	global_store_dwordx4 v5, v[246:249], s[58:59]
	v_add_u32_e32 v5, 0xc00, v5
	v_lshlrev_b32_e32 v96, 16, v52
	v_and_b32_e32 v97, 0xffff0000, v52
	v_lshlrev_b32_e32 v98, 16, v53
	v_and_b32_e32 v99, 0xffff0000, v53
	v_lshlrev_b32_e32 v100, 16, v54
	v_and_b32_e32 v101, 0xffff0000, v54
	v_lshlrev_b32_e32 v102, 16, v55
	v_and_b32_e32 v103, 0xffff0000, v55
	v_add_f32_e32 v136, v80, v96
	v_add_f32_e32 v137, v81, v97
	v_add_f32_e32 v138, v82, v98
	v_add_f32_e32 v139, v83, v99
	v_add_f32_e32 v140, v84, v100
	v_add_f32_e32 v141, v85, v101
	v_add_f32_e32 v142, v86, v102
	v_add_f32_e32 v143, v87, v103
	v_fma_f32 v136, v136, 0.5, -v88
	v_fma_f32 v137, v137, 0.5, -v89
	v_fma_f32 v138, v138, 0.5, -v90
	v_fma_f32 v139, v139, 0.5, -v91
	v_fma_f32 v140, v140, 0.5, -v92
	v_fma_f32 v141, v141, 0.5, -v93
	v_fma_f32 v142, v142, 0.5, -v94
	v_fma_f32 v143, v143, 0.5, -v95
	v_fma_f32 v128, v104, v136, v88
	v_fma_f32 v129, v105, v137, v89
	v_fma_f32 v130, v106, v138, v90
	v_fma_f32 v131, v107, v139, v91
	v_fma_f32 v132, v108, v140, v92
	v_fma_f32 v133, v109, v141, v93
	v_fma_f32 v134, v110, v142, v94
	v_fma_f32 v135, v111, v143, v95
	v_cvt_pk_bf16_f32 v246, v128, v129
	v_cvt_pk_bf16_f32 v247, v130, v131
	v_cvt_pk_bf16_f32 v248, v132, v133
	v_cvt_pk_bf16_f32 v249, v134, v135
	global_store_dwordx4 v5, v[246:249], s[58:59]
	v_add_u32_e32 v5, 0xc00, v5
	v_lshlrev_b32_e32 v80, 16, v56
	v_and_b32_e32 v81, 0xffff0000, v56
	v_lshlrev_b32_e32 v82, 16, v57
	v_and_b32_e32 v83, 0xffff0000, v57
	v_lshlrev_b32_e32 v84, 16, v58
	v_and_b32_e32 v85, 0xffff0000, v58
	v_lshlrev_b32_e32 v86, 16, v59
	v_and_b32_e32 v87, 0xffff0000, v59
	v_add_f32_e32 v136, v88, v80
	v_add_f32_e32 v137, v89, v81
	v_add_f32_e32 v138, v90, v82
	v_add_f32_e32 v139, v91, v83
	v_add_f32_e32 v140, v92, v84
	v_add_f32_e32 v141, v93, v85
	v_add_f32_e32 v142, v94, v86
	v_add_f32_e32 v143, v95, v87
	v_fma_f32 v136, v136, 0.5, -v96
	v_fma_f32 v137, v137, 0.5, -v97
	v_fma_f32 v138, v138, 0.5, -v98
	v_fma_f32 v139, v139, 0.5, -v99
	v_fma_f32 v140, v140, 0.5, -v100
	v_fma_f32 v141, v141, 0.5, -v101
	v_fma_f32 v142, v142, 0.5, -v102
	v_fma_f32 v143, v143, 0.5, -v103
	v_fma_f32 v128, v104, v136, v96
	v_fma_f32 v129, v105, v137, v97
	v_fma_f32 v130, v106, v138, v98
	v_fma_f32 v131, v107, v139, v99
	v_fma_f32 v132, v108, v140, v100
	v_fma_f32 v133, v109, v141, v101
	v_fma_f32 v134, v110, v142, v102
	v_fma_f32 v135, v111, v143, v103
	v_cvt_pk_bf16_f32 v246, v128, v129
	v_cvt_pk_bf16_f32 v247, v130, v131
	v_cvt_pk_bf16_f32 v248, v132, v133
	v_cvt_pk_bf16_f32 v249, v134, v135
	global_store_dwordx4 v5, v[246:249], s[58:59]
	v_add_u32_e32 v5, 0xc00, v5
	v_lshlrev_b32_e32 v88, 16, v60
	v_and_b32_e32 v89, 0xffff0000, v60
	v_lshlrev_b32_e32 v90, 16, v61
	v_and_b32_e32 v91, 0xffff0000, v61
	v_lshlrev_b32_e32 v92, 16, v62
	v_and_b32_e32 v93, 0xffff0000, v62
	v_lshlrev_b32_e32 v94, 16, v63
	v_and_b32_e32 v95, 0xffff0000, v63
	v_add_f32_e32 v136, v96, v88
	v_add_f32_e32 v137, v97, v89
	v_add_f32_e32 v138, v98, v90
	v_add_f32_e32 v139, v99, v91
	v_add_f32_e32 v140, v100, v92
	v_add_f32_e32 v141, v101, v93
	v_add_f32_e32 v142, v102, v94
	v_add_f32_e32 v143, v103, v95
	v_fma_f32 v136, v136, 0.5, -v80
	v_fma_f32 v137, v137, 0.5, -v81
	v_fma_f32 v138, v138, 0.5, -v82
	v_fma_f32 v139, v139, 0.5, -v83
	v_fma_f32 v140, v140, 0.5, -v84
	v_fma_f32 v141, v141, 0.5, -v85
	v_fma_f32 v142, v142, 0.5, -v86
	v_fma_f32 v143, v143, 0.5, -v87
	v_fma_f32 v128, v104, v136, v80
	v_fma_f32 v129, v105, v137, v81
	v_fma_f32 v130, v106, v138, v82
	v_fma_f32 v131, v107, v139, v83
	v_fma_f32 v132, v108, v140, v84
	v_fma_f32 v133, v109, v141, v85
	v_fma_f32 v134, v110, v142, v86
	v_fma_f32 v135, v111, v143, v87
	v_cvt_pk_bf16_f32 v246, v128, v129
	v_cvt_pk_bf16_f32 v247, v130, v131
	v_cvt_pk_bf16_f32 v248, v132, v133
	v_cvt_pk_bf16_f32 v249, v134, v135
	global_store_dwordx4 v5, v[246:249], s[58:59]
	v_add_u32_e32 v5, 0xc00, v5
	v_lshlrev_b32_e32 v96, 16, v64
	v_and_b32_e32 v97, 0xffff0000, v64
	v_lshlrev_b32_e32 v98, 16, v65
	v_and_b32_e32 v99, 0xffff0000, v65
	v_lshlrev_b32_e32 v100, 16, v66
	v_and_b32_e32 v101, 0xffff0000, v66
	v_lshlrev_b32_e32 v102, 16, v67
	v_and_b32_e32 v103, 0xffff0000, v67
	v_add_f32_e32 v136, v80, v96
	v_add_f32_e32 v137, v81, v97
	v_add_f32_e32 v138, v82, v98
	v_add_f32_e32 v139, v83, v99
	v_add_f32_e32 v140, v84, v100
	v_add_f32_e32 v141, v85, v101
	v_add_f32_e32 v142, v86, v102
	v_add_f32_e32 v143, v87, v103
	v_fma_f32 v136, v136, 0.5, -v88
	v_fma_f32 v137, v137, 0.5, -v89
	v_fma_f32 v138, v138, 0.5, -v90
	v_fma_f32 v139, v139, 0.5, -v91
	v_fma_f32 v140, v140, 0.5, -v92
	v_fma_f32 v141, v141, 0.5, -v93
	v_fma_f32 v142, v142, 0.5, -v94
	v_fma_f32 v143, v143, 0.5, -v95
	v_fma_f32 v128, v104, v136, v88
	v_fma_f32 v129, v105, v137, v89
	v_fma_f32 v130, v106, v138, v90
	v_fma_f32 v131, v107, v139, v91
	v_fma_f32 v132, v108, v140, v92
	v_fma_f32 v133, v109, v141, v93
	v_fma_f32 v134, v110, v142, v94
	v_fma_f32 v135, v111, v143, v95
	v_cvt_pk_bf16_f32 v246, v128, v129
	v_cvt_pk_bf16_f32 v247, v130, v131
	v_cvt_pk_bf16_f32 v248, v132, v133
	v_cvt_pk_bf16_f32 v249, v134, v135
; __device__ __forceinline__ void unpack8(const u32x4 w, float (&f)[8]) { f[0] = bflo(w.x); f[1] = bfhi(w.x); f[2] = bflo(w.y); f[3] = bfhi(w.y); f[4] = bflo(w.z); f[5] = bfhi(w.z); f[6] = bflo(w.w); f[7] = bfhi(w.w); }
; __device__ __forceinline__ u32x4 pack8(const float (&f)[8]) { u32x4 o; o.x = pk2(f[0], f[1]); o.y = pk2(f[2], f[3]); o.z = pk2(f[4], f[5]); o.w = pk2(f[6], f[7]); return o; }
; template <int CH> __device__ __forceinline__ void p2_rwkv_chunk(const Params& p, int t0, int lane) {
;     ...
;     const bf16_t* zc = (const bf16_t*)(ws + WS_Z) + (size_t)t0 * ZLD + c;
;     float mu[8], kq[8];
;     { const f32x4 m0 = *(const f32x4*)(p.in[8] + c), m1 = *(const f32x4*)(p.in[8] + c + 4);
; #pragma unroll
;       for (int i = 0; i < 4; ++i) { mu[i] = m0[i]; mu[4 + i] = m1[i]; } }
;     if (CH == 1) { const f32x4 q0 = *(const f32x4*)(p.in[14] + c - 512), q1 = *(const f32x4*)(p.in[14] + c - 512 + 4);
; #pragma unroll
;         for (int i = 0; i < 4; ++i) { kq[i] = q0[i]; kq[4 + i] = q1[i]; } }
;     float P[8], C[8], N[8];
;     if ((t0 & (T_SEQ - 1)) != 0) unpack8(__builtin_nontemporal_load((const u32x4*)(zc - ZLD)), P); else {
; #pragma unroll
;         for (int i = 0; i < 8; ++i) P[i] = 0.f; }
;     unpack8(__builtin_nontemporal_load((const u32x4*)(zc)), C);
;     u32x4 raw = __builtin_nontemporal_load((const u32x4*)(zc + ZLD));
;     ...
;     for (int i = 0; i < 16; ++i) {
;         const int t = t0 + i; const bool hasn = (t & (T_SEQ - 1)) != T_SEQ - 1;
;         if (hasn) unpack8(raw, N); else {
; #pragma unroll
;             for (int q = 0; q < 8; ++q) N[q] = 0.f; }
;         if (i < 15 && ((t + 1) & (T_SEQ - 1)) != T_SEQ - 1) raw = __builtin_nontemporal_load((const u32x4*)(zc + (size_t)(i + 2) * ZLD));
;         float zs[8];
; #pragma unroll
;         for (int q = 0; q < 8; ++q) zs[q] = C[q] + mu[q] * (0.5f * (P[q] + N[q]) - C[q]);
;         if (CH < 3) {
;             *(u32x4*)(RKV + (size_t)t * 1536 + c) = pack8(zs);
	global_store_dwordx4 v5, v[246:249], s[58:59]
	v_add_u32_e32 v5, 0xc00, v5
	v_lshlrev_b32_e32 v80, 16, v68
	v_and_b32_e32 v81, 0xffff0000, v68
	v_lshlrev_b32_e32 v82, 16, v69
	v_and_b32_e32 v83, 0xffff0000, v69
	v_lshlrev_b32_e32 v84, 16, v70
	v_and_b32_e32 v85, 0xffff0000, v70
	v_lshlrev_b32_e32 v86, 16, v71
	v_and_b32_e32 v87, 0xffff0000, v71
	v_add_f32_e32 v136, v88, v80
	v_add_f32_e32 v137, v89, v81
	v_add_f32_e32 v138, v90, v82
	v_add_f32_e32 v139, v91, v83
	v_add_f32_e32 v140, v92, v84
	v_add_f32_e32 v141, v93, v85
	v_add_f32_e32 v142, v94, v86
	v_add_f32_e32 v143, v95, v87
	v_fma_f32 v136, v136, 0.5, -v96
	v_fma_f32 v137, v137, 0.5, -v97
	v_fma_f32 v138, v138, 0.5, -v98
	v_fma_f32 v139, v139, 0.5, -v99
	v_fma_f32 v140, v140, 0.5, -v100
	v_fma_f32 v141, v141, 0.5, -v101
	v_fma_f32 v142, v142, 0.5, -v102
	v_fma_f32 v143, v143, 0.5, -v103
	v_fma_f32 v128, v104, v136, v96
	v_fma_f32 v129, v105, v137, v97
	v_fma_f32 v130, v106, v138, v98
	v_fma_f32 v131, v107, v139, v99
	v_fma_f32 v132, v108, v140, v100
	v_fma_f32 v133, v109, v141, v101
	v_fma_f32 v134, v110, v142, v102
	v_fma_f32 v135, v111, v143, v103
	v_cvt_pk_bf16_f32 v246, v128, v129
	v_cvt_pk_bf16_f32 v247, v130, v131
	v_cvt_pk_bf16_f32 v248, v132, v133
	v_cvt_pk_bf16_f32 v249, v134, v135
	global_store_dwordx4 v5, v[246:249], s[58:59]
	v_add_u32_e32 v5, 0xc00, v5
	v_lshlrev_b32_e32 v88, 16, v72
	v_and_b32_e32 v89, 0xffff0000, v72
	v_lshlrev_b32_e32 v90, 16, v73
	v_and_b32_e32 v91, 0xffff0000, v73
	v_lshlrev_b32_e32 v92, 16, v74
	v_and_b32_e32 v93, 0xffff0000, v74
	v_lshlrev_b32_e32 v94, 16, v75
	v_and_b32_e32 v95, 0xffff0000, v75
	v_add_f32_e32 v136, v96, v88
	v_add_f32_e32 v137, v97, v89
	v_add_f32_e32 v138, v98, v90
	v_add_f32_e32 v139, v99, v91
	v_add_f32_e32 v140, v100, v92
	v_add_f32_e32 v141, v101, v93
	v_add_f32_e32 v142, v102, v94
	v_add_f32_e32 v143, v103, v95
	v_fma_f32 v136, v136, 0.5, -v80
	v_fma_f32 v137, v137, 0.5, -v81
	v_fma_f32 v138, v138, 0.5, -v82
	v_fma_f32 v139, v139, 0.5, -v83
	v_fma_f32 v140, v140, 0.5, -v84
	v_fma_f32 v141, v141, 0.5, -v85
	v_fma_f32 v142, v142, 0.5, -v86
	v_fma_f32 v143, v143, 0.5, -v87
	v_fma_f32 v128, v104, v136, v80
	v_fma_f32 v129, v105, v137, v81
	v_fma_f32 v130, v106, v138, v82
	v_fma_f32 v131, v107, v139, v83
	v_fma_f32 v132, v108, v140, v84
	v_fma_f32 v133, v109, v141, v85
	v_fma_f32 v134, v110, v142, v86
	v_fma_f32 v135, v111, v143, v87
	v_cvt_pk_bf16_f32 v246, v128, v129
	v_cvt_pk_bf16_f32 v247, v130, v131
	v_cvt_pk_bf16_f32 v248, v132, v133
	v_cvt_pk_bf16_f32 v249, v134, v135
	global_store_dwordx4 v5, v[246:249], s[58:59]
	v_add_u32_e32 v5, 0xc00, v5
	s_cmp_eq_u32 s67, 0
	s_cbranch_scc1 .Lp2_nz_4
	v_mov_b32_e32 v76, 0
	v_mov_b32_e32 v77, 0
	v_mov_b32_e32 v78, 0
	v_mov_b32_e32 v79, 0
.Lp2_nz_4:
	v_lshlrev_b32_e32 v96, 16, v76
	v_and_b32_e32 v97, 0xffff0000, v76
	v_lshlrev_b32_e32 v98, 16, v77
	v_and_b32_e32 v99, 0xffff0000, v77
	v_lshlrev_b32_e32 v100, 16, v78
	v_and_b32_e32 v101, 0xffff0000, v78
	v_lshlrev_b32_e32 v102, 16, v79
	v_and_b32_e32 v103, 0xffff0000, v79
	v_add_f32_e32 v136, v80, v96
	v_add_f32_e32 v137, v81, v97
	v_add_f32_e32 v138, v82, v98
	v_add_f32_e32 v139, v83, v99
	v_add_f32_e32 v140, v84, v100
	v_add_f32_e32 v141, v85, v101
	v_add_f32_e32 v142, v86, v102
	v_add_f32_e32 v143, v87, v103
	v_fma_f32 v136, v136, 0.5, -v88
	v_fma_f32 v137, v137, 0.5, -v89
	v_fma_f32 v138, v138, 0.5, -v90
	v_fma_f32 v139, v139, 0.5, -v91
	v_fma_f32 v140, v140, 0.5, -v92
	v_fma_f32 v141, v141, 0.5, -v93
	v_fma_f32 v142, v142, 0.5, -v94
	v_fma_f32 v143, v143, 0.5, -v95
	v_fma_f32 v128, v104, v136, v88
	v_fma_f32 v129, v105, v137, v89
	v_fma_f32 v130, v106, v138, v90
	v_fma_f32 v131, v107, v139, v91
	v_fma_f32 v132, v108, v140, v92
	v_fma_f32 v133, v109, v141, v93
	v_fma_f32 v134, v110, v142, v94
	v_fma_f32 v135, v111, v143, v95
	v_cvt_pk_bf16_f32 v246, v128, v129
	v_cvt_pk_bf16_f32 v247, v130, v131
	v_cvt_pk_bf16_f32 v248, v132, v133
	v_cvt_pk_bf16_f32 v249, v134, v135
	global_store_dwordx4 v5, v[246:249], s[58:59]
	v_add_u32_e32 v5, 0xc00, v5
	s_mov_b32 s98, 0x800
	s_mov_b32 s99, 0
	v_lshl_add_u64 v[2:3], v[250:251], 0, s[98:99]
	global_load_dwordx4 v[104:107], v[2:3], off
	global_load_dwordx4 v[108:111], v[2:3], off offset:16
	v_lshlrev_b32_e32 v1, 5, v0
	global_load_dwordx4 v[112:115], v1, s[28:29]
	global_load_dwordx4 v[116:119], v1, s[28:29] offset:16
	s_mul_i32 s63, s62, 0x1c00
	s_add_u32 s63, s63, 0x7000800
	v_lshl_add_u32 v4, v0, 4, s63
	v_add_u32_e32 v1, 0xffffe400, v4
	s_cmp_lg_u32 s66, 0
	s_cselect_b64 vcc, -1, 0
	s_nop 1
	v_cndmask_b32_e32 v1, v1, v4, vcc
	global_load_dwordx4 v[8:11], v1, s[58:59] nt
	global_load_dwordx4 v[12:15], v4, s[58:59] nt
	v_mov_b32_e32 v1, v4
	v_add_u32_e32 v1, 0x1c00, v1
	global_load_dwordx4 v[16:19], v1, s[58:59] nt
	v_add_u32_e32 v1, 0x1c00, v1
	global_load_dwordx4 v[20:23], v1, s[58:59] nt
	v_add_u32_e32 v1, 0x1c00, v1
	global_load_dwordx4 v[24:27], v1, s[58:59] nt
	v_add_u32_e32 v1, 0x1c00, v1
	global_load_dwordx4 v[28:31], v1, s[58:59] nt
	v_add_u32_e32 v1, 0x1c00, v1
	global_load_dwordx4 v[32:35], v1, s[58:59] nt
	v_add_u32_e32 v1, 0x1c00, v1
	global_load_dwordx4 v[36:39], v1, s[58:59] nt
	v_add_u32_e32 v1, 0x1c00, v1
	global_load_dwordx4 v[40:43], v1, s[58:59] nt
	v_add_u32_e32 v1, 0x1c00, v1
	global_load_dwordx4 v[44:47], v1, s[58:59] nt
	v_add_u32_e32 v1, 0x1c00, v1
	global_load_dwordx4 v[48:51], v1, s[58:59] nt
	v_add_u32_e32 v1, 0x1c00, v1
	global_load_dwordx4 v[52:55], v1, s[58:59] nt
	v_add_u32_e32 v1, 0x1c00, v1
	global_load_dwordx4 v[56:59], v1, s[58:59] nt
	v_add_u32_e32 v1, 0x1c00, v1
	global_load_dwordx4 v[60:63], v1, s[58:59] nt
	v_add_u32_e32 v1, 0x1c00, v1
	global_load_dwordx4 v[64:67], v1, s[58:59] nt
	v_add_u32_e32 v1, 0x1c00, v1
	global_load_dwordx4 v[68:71], v1, s[58:59] nt
	v_add_u32_e32 v1, 0x1c00, v1
	global_load_dwordx4 v[72:75], v1, s[58:59] nt
	v_add_u32_e32 v1, 0x1c00, v1
	s_cmp_lg_u32 s67, 0
	s_cselect_b64 vcc, -1, 0
	s_nop 1
	v_cndmask_b32_e32 v1, v1, v4, vcc
	global_load_dwordx4 v[76:79], v1, s[58:59] nt
	s_mul_i32 s63, s62, 0xc00
	s_add_u32 s63, s63, 0x15000400
	v_lshl_add_u32 v5, v0, 4, s63
	s_lshl_b32 s63, s62, 5
	s_add_u32 s63, s63, 0x2e00000
	v_lshrrev_b32_e32 v6, 3, v0
	v_lshl_add_u32 v6, v6, 2, s63
	v_and_b32_e32 v151, 7, v0
	v_cmp_eq_u32_e64 s[64:65], 0, v151
	s_waitcnt vmcnt(18)
	s_cmp_eq_u32 s66, 0
	s_cbranch_scc1 .Lp2_nz_5
	v_mov_b32_e32 v168, 0
	v_mov_b32_e32 v169, 0
	v_mov_b32_e32 v170, 0
	v_mov_b32_e32 v171, 0
; __device__ __forceinline__ void unpack8(const u32x4 w, float (&f)[8]) { f[0] = bflo(w.x); f[1] = bfhi(w.x); f[2] = bflo(w.y); f[3] = bfhi(w.y); f[4] = bflo(w.z); f[5] = bfhi(w.z); f[6] = bflo(w.w); f[7] = bfhi(w.w); }
; __device__ __forceinline__ u32x4 pack8(const float (&f)[8]) { u32x4 o; o.x = pk2(f[0], f[1]); o.y = pk2(f[2], f[3]); o.z = pk2(f[4], f[5]); o.w = pk2(f[6], f[7]); return o; }
; template <int CH> __device__ __forceinline__ void p2_rwkv_chunk(const Params& p, int t0, int lane) {
;     ...
;     for (int i = 0; i < 16; ++i) {
;         const int t = t0 + i; const bool hasn = (t & (T_SEQ - 1)) != T_SEQ - 1;
;         if (hasn) unpack8(raw, N); else {
; #pragma unroll
;             for (int q = 0; q < 8; ++q) N[q] = 0.f; }
;         if (i < 15 && ((t + 1) & (T_SEQ - 1)) != T_SEQ - 1) raw = __builtin_nontemporal_load((const u32x4*)(zc + (size_t)(i + 2) * ZLD));
;         float zs[8];
; #pragma unroll
;         for (int q = 0; q < 8; ++q) zs[q] = C[q] + mu[q] * (0.5f * (P[q] + N[q]) - C[q]);
;         if (CH < 3) {
;             *(u32x4*)(RKV + (size_t)t * 1536 + c) = pack8(zs);
;             if (CH == 1) { float s2 = 0.f;
; #pragma unroll
;                 for (int q = 0; q < 8; ++q) { const float v = zs[q] * kq[q]; s2 += v * v; }
;                 s2 = red8s(s2);
;                 if ((lane & 7) == 0) RINV[t * 8 + (lane >> 3)] = rsqrtf(fmaxf(s2, 1e-24f)); }
.Lp2_nz_5:
	v_lshlrev_b32_e32 v80, 16, v168
	v_and_b32_e32 v81, 0xffff0000, v168
	v_lshlrev_b32_e32 v82, 16, v169
	v_and_b32_e32 v83, 0xffff0000, v169
	v_lshlrev_b32_e32 v84, 16, v170
	v_and_b32_e32 v85, 0xffff0000, v170
	v_lshlrev_b32_e32 v86, 16, v171
	v_and_b32_e32 v87, 0xffff0000, v171
	v_lshlrev_b32_e32 v88, 16, v172
	v_and_b32_e32 v89, 0xffff0000, v172
	v_lshlrev_b32_e32 v90, 16, v173
	v_and_b32_e32 v91, 0xffff0000, v173
	v_lshlrev_b32_e32 v92, 16, v174
	v_and_b32_e32 v93, 0xffff0000, v174
	v_lshlrev_b32_e32 v94, 16, v175
	v_and_b32_e32 v95, 0xffff0000, v175
	v_lshlrev_b32_e32 v96, 16, v176
	v_and_b32_e32 v97, 0xffff0000, v176
	v_lshlrev_b32_e32 v98, 16, v177
	v_and_b32_e32 v99, 0xffff0000, v177
	v_lshlrev_b32_e32 v100, 16, v178
	v_and_b32_e32 v101, 0xffff0000, v178
	v_lshlrev_b32_e32 v102, 16, v179
	v_and_b32_e32 v103, 0xffff0000, v179
	v_add_f32_e32 v136, v80, v96
	v_add_f32_e32 v137, v81, v97
	v_add_f32_e32 v138, v82, v98
	v_add_f32_e32 v139, v83, v99
	v_add_f32_e32 v140, v84, v100
	v_add_f32_e32 v141, v85, v101
	v_add_f32_e32 v142, v86, v102
	v_add_f32_e32 v143, v87, v103
	v_fma_f32 v136, v136, 0.5, -v88
	v_fma_f32 v137, v137, 0.5, -v89
	v_fma_f32 v138, v138, 0.5, -v90
	v_fma_f32 v139, v139, 0.5, -v91
	v_fma_f32 v140, v140, 0.5, -v92
	v_fma_f32 v141, v141, 0.5, -v93
	v_fma_f32 v142, v142, 0.5, -v94
	v_fma_f32 v143, v143, 0.5, -v95
	v_fma_f32 v128, v104, v136, v88
	v_fma_f32 v129, v105, v137, v89
	v_fma_f32 v130, v106, v138, v90
	v_fma_f32 v131, v107, v139, v91
	v_fma_f32 v132, v108, v140, v92
	v_fma_f32 v133, v109, v141, v93
	v_fma_f32 v134, v110, v142, v94
	v_fma_f32 v135, v111, v143, v95
	v_cvt_pk_bf16_f32 v246, v128, v129
	v_cvt_pk_bf16_f32 v247, v130, v131
	v_cvt_pk_bf16_f32 v248, v132, v133
	v_cvt_pk_bf16_f32 v249, v134, v135
	global_store_dwordx4 v5, v[246:249], s[58:59]
	v_add_u32_e32 v5, 0xc00, v5
	v_mul_f32_e32 v136, v128, v112
	v_mul_f32_e32 v137, v129, v113
	v_mul_f32_e32 v138, v130, v114
	v_mul_f32_e32 v139, v131, v115
	v_mul_f32_e32 v140, v132, v116
	v_mul_f32_e32 v141, v133, v117
	v_mul_f32_e32 v142, v134, v118
	v_mul_f32_e32 v143, v135, v119
	v_mul_f32_e32 v144, v136, v136
	v_fmac_f32_e32 v144, v137, v137
	v_fmac_f32_e32 v144, v138, v138
	v_fmac_f32_e32 v144, v139, v139
	v_fmac_f32_e32 v144, v140, v140
	v_fmac_f32_e32 v144, v141, v141
	v_fmac_f32_e32 v144, v142, v142
	v_fmac_f32_e32 v144, v143, v143
	s_nop 1
	v_add_f32_dpp v144, v144, v144 quad_perm:[1,0,3,2] row_mask:0xf bank_mask:0xf bound_ctrl:1
	s_nop 1
	v_add_f32_dpp v144, v144, v144 quad_perm:[2,3,0,1] row_mask:0xf bank_mask:0xf bound_ctrl:1
	s_nop 1
	v_add_f32_dpp v144, v144, v144 row_half_mirror row_mask:0xf bank_mask:0xf bound_ctrl:1
	v_max_f32_e32 v144, 0x179abe15, v144
	v_rsq_f32_e32 v144, v144
	s_mov_b64 s[42:43], exec
	s_and_b64 exec, exec, s[64:65]
	global_store_dword v6, v144, s[58:59]
	s_mov_b64 exec, s[42:43]
	v_add_u32_e32 v6, 32, v6
	v_lshlrev_b32_e32 v80, 16, v180
	v_and_b32_e32 v81, 0xffff0000, v180
	v_lshlrev_b32_e32 v82, 16, v181
	v_and_b32_e32 v83, 0xffff0000, v181
	v_lshlrev_b32_e32 v84, 16, v182
	v_and_b32_e32 v85, 0xffff0000, v182
	v_lshlrev_b32_e32 v86, 16, v183
	v_and_b32_e32 v87, 0xffff0000, v183
	v_add_f32_e32 v136, v88, v80
	v_add_f32_e32 v137, v89, v81
	v_add_f32_e32 v138, v90, v82
	v_add_f32_e32 v139, v91, v83
	v_add_f32_e32 v140, v92, v84
	v_add_f32_e32 v141, v93, v85
	v_add_f32_e32 v142, v94, v86
	v_add_f32_e32 v143, v95, v87
	v_fma_f32 v136, v136, 0.5, -v96
	v_fma_f32 v137, v137, 0.5, -v97
	v_fma_f32 v138, v138, 0.5, -v98
	v_fma_f32 v139, v139, 0.5, -v99
	v_fma_f32 v140, v140, 0.5, -v100
	v_fma_f32 v141, v141, 0.5, -v101
	v_fma_f32 v142, v142, 0.5, -v102
	v_fma_f32 v143, v143, 0.5, -v103
	v_fma_f32 v128, v104, v136, v96
	v_fma_f32 v129, v105, v137, v97
	v_fma_f32 v130, v106, v138, v98
	v_fma_f32 v131, v107, v139, v99
	v_fma_f32 v132, v108, v140, v100
	v_fma_f32 v133, v109, v141, v101
	v_fma_f32 v134, v110, v142, v102
	v_fma_f32 v135, v111, v143, v103
	v_cvt_pk_bf16_f32 v246, v128, v129
	v_cvt_pk_bf16_f32 v247, v130, v131
	v_cvt_pk_bf16_f32 v248, v132, v133
	v_cvt_pk_bf16_f32 v249, v134, v135
	global_store_dwordx4 v5, v[246:249], s[58:59]
	v_add_u32_e32 v5, 0xc00, v5
	v_mul_f32_e32 v136, v128, v112
	v_mul_f32_e32 v137, v129, v113
	v_mul_f32_e32 v138, v130, v114
	v_mul_f32_e32 v139, v131, v115
	v_mul_f32_e32 v140, v132, v116
	v_mul_f32_e32 v141, v133, v117
	v_mul_f32_e32 v142, v134, v118
	v_mul_f32_e32 v143, v135, v119
	v_mul_f32_e32 v144, v136, v136
	v_fmac_f32_e32 v144, v137, v137
	v_fmac_f32_e32 v144, v138, v138
	v_fmac_f32_e32 v144, v139, v139
	v_fmac_f32_e32 v144, v140, v140
	v_fmac_f32_e32 v144, v141, v141
	v_fmac_f32_e32 v144, v142, v142
	v_fmac_f32_e32 v144, v143, v143
	s_nop 1
	v_add_f32_dpp v144, v144, v144 quad_perm:[1,0,3,2] row_mask:0xf bank_mask:0xf bound_ctrl:1
	s_nop 1
	v_add_f32_dpp v144, v144, v144 quad_perm:[2,3,0,1] row_mask:0xf bank_mask:0xf bound_ctrl:1
	s_nop 1
	v_add_f32_dpp v144, v144, v144 row_half_mirror row_mask:0xf bank_mask:0xf bound_ctrl:1
	v_max_f32_e32 v144, 0x179abe15, v144
	v_rsq_f32_e32 v144, v144
	s_mov_b64 s[42:43], exec
	s_and_b64 exec, exec, s[64:65]
	global_store_dword v6, v144, s[58:59]
	s_mov_b64 exec, s[42:43]
	v_add_u32_e32 v6, 32, v6
	v_lshlrev_b32_e32 v88, 16, v184
	v_and_b32_e32 v89, 0xffff0000, v184
	v_lshlrev_b32_e32 v90, 16, v185
	v_and_b32_e32 v91, 0xffff0000, v185
	v_lshlrev_b32_e32 v92, 16, v186
	v_and_b32_e32 v93, 0xffff0000, v186
	v_lshlrev_b32_e32 v94, 16, v187
	v_and_b32_e32 v95, 0xffff0000, v187
	v_add_f32_e32 v136, v96, v88
	v_add_f32_e32 v137, v97, v89
	v_add_f32_e32 v138, v98, v90
	v_add_f32_e32 v139, v99, v91
	v_add_f32_e32 v140, v100, v92
	v_add_f32_e32 v141, v101, v93
; __device__ __forceinline__ void unpack8(const u32x4 w, float (&f)[8]) { f[0] = bflo(w.x); f[1] = bfhi(w.x); f[2] = bflo(w.y); f[3] = bfhi(w.y); f[4] = bflo(w.z); f[5] = bfhi(w.z); f[6] = bflo(w.w); f[7] = bfhi(w.w); }
; __device__ __forceinline__ u32x4 pack8(const float (&f)[8]) { u32x4 o; o.x = pk2(f[0], f[1]); o.y = pk2(f[2], f[3]); o.z = pk2(f[4], f[5]); o.w = pk2(f[6], f[7]); return o; }
; template <int CH> __device__ __forceinline__ void p2_rwkv_chunk(const Params& p, int t0, int lane) {
;     ...
;     for (int i = 0; i < 16; ++i) {
;         const int t = t0 + i; const bool hasn = (t & (T_SEQ - 1)) != T_SEQ - 1;
;         if (hasn) unpack8(raw, N); else {
; #pragma unroll
;             for (int q = 0; q < 8; ++q) N[q] = 0.f; }
;         if (i < 15 && ((t + 1) & (T_SEQ - 1)) != T_SEQ - 1) raw = __builtin_nontemporal_load((const u32x4*)(zc + (size_t)(i + 2) * ZLD));
;         float zs[8];
; #pragma unroll
;         for (int q = 0; q < 8; ++q) zs[q] = C[q] + mu[q] * (0.5f * (P[q] + N[q]) - C[q]);
;         if (CH < 3) {
;             *(u32x4*)(RKV + (size_t)t * 1536 + c) = pack8(zs);
;             if (CH == 1) { float s2 = 0.f;
; #pragma unroll
;                 for (int q = 0; q < 8; ++q) { const float v = zs[q] * kq[q]; s2 += v * v; }
;                 s2 = red8s(s2);
;                 if ((lane & 7) == 0) RINV[t * 8 + (lane >> 3)] = rsqrtf(fmaxf(s2, 1e-24f)); }
	v_add_f32_e32 v142, v102, v94
	v_add_f32_e32 v143, v103, v95
	v_fma_f32 v136, v136, 0.5, -v80
	v_fma_f32 v137, v137, 0.5, -v81
	v_fma_f32 v138, v138, 0.5, -v82
	v_fma_f32 v139, v139, 0.5, -v83
	v_fma_f32 v140, v140, 0.5, -v84
	v_fma_f32 v141, v141, 0.5, -v85
	v_fma_f32 v142, v142, 0.5, -v86
	v_fma_f32 v143, v143, 0.5, -v87
	v_fma_f32 v128, v104, v136, v80
	v_fma_f32 v129, v105, v137, v81
	v_fma_f32 v130, v106, v138, v82
	v_fma_f32 v131, v107, v139, v83
	v_fma_f32 v132, v108, v140, v84
	v_fma_f32 v133, v109, v141, v85
	v_fma_f32 v134, v110, v142, v86
	v_fma_f32 v135, v111, v143, v87
	v_cvt_pk_bf16_f32 v246, v128, v129
	v_cvt_pk_bf16_f32 v247, v130, v131
	v_cvt_pk_bf16_f32 v248, v132, v133
	v_cvt_pk_bf16_f32 v249, v134, v135
	global_store_dwordx4 v5, v[246:249], s[58:59]
	v_add_u32_e32 v5, 0xc00, v5
	v_mul_f32_e32 v136, v128, v112
	v_mul_f32_e32 v137, v129, v113
	v_mul_f32_e32 v138, v130, v114
	v_mul_f32_e32 v139, v131, v115
	v_mul_f32_e32 v140, v132, v116
	v_mul_f32_e32 v141, v133, v117
	v_mul_f32_e32 v142, v134, v118
	v_mul_f32_e32 v143, v135, v119
	v_mul_f32_e32 v144, v136, v136
	v_fmac_f32_e32 v144, v137, v137
	v_fmac_f32_e32 v144, v138, v138
	v_fmac_f32_e32 v144, v139, v139
	v_fmac_f32_e32 v144, v140, v140
	v_fmac_f32_e32 v144, v141, v141
	v_fmac_f32_e32 v144, v142, v142
	v_fmac_f32_e32 v144, v143, v143
	s_nop 1
	v_add_f32_dpp v144, v144, v144 quad_perm:[1,0,3,2] row_mask:0xf bank_mask:0xf bound_ctrl:1
	s_nop 1
	v_add_f32_dpp v144, v144, v144 quad_perm:[2,3,0,1] row_mask:0xf bank_mask:0xf bound_ctrl:1
	s_nop 1
	v_add_f32_dpp v144, v144, v144 row_half_mirror row_mask:0xf bank_mask:0xf bound_ctrl:1
	v_max_f32_e32 v144, 0x179abe15, v144
	v_rsq_f32_e32 v144, v144
	s_mov_b64 s[42:43], exec
	s_and_b64 exec, exec, s[64:65]
	global_store_dword v6, v144, s[58:59]
	s_mov_b64 exec, s[42:43]
	v_add_u32_e32 v6, 32, v6
	v_lshlrev_b32_e32 v96, 16, v188
	v_and_b32_e32 v97, 0xffff0000, v188
	v_lshlrev_b32_e32 v98, 16, v189
	v_and_b32_e32 v99, 0xffff0000, v189
	v_lshlrev_b32_e32 v100, 16, v190
	v_and_b32_e32 v101, 0xffff0000, v190
	v_lshlrev_b32_e32 v102, 16, v191
	v_and_b32_e32 v103, 0xffff0000, v191
	v_add_f32_e32 v136, v80, v96
	v_add_f32_e32 v137, v81, v97
	v_add_f32_e32 v138, v82, v98
	v_add_f32_e32 v139, v83, v99
	v_add_f32_e32 v140, v84, v100
	v_add_f32_e32 v141, v85, v101
	v_add_f32_e32 v142, v86, v102
	v_add_f32_e32 v143, v87, v103
	v_fma_f32 v136, v136, 0.5, -v88
	v_fma_f32 v137, v137, 0.5, -v89
	v_fma_f32 v138, v138, 0.5, -v90
	v_fma_f32 v139, v139, 0.5, -v91
	v_fma_f32 v140, v140, 0.5, -v92
	v_fma_f32 v141, v141, 0.5, -v93
	v_fma_f32 v142, v142, 0.5, -v94
	v_fma_f32 v143, v143, 0.5, -v95
	v_fma_f32 v128, v104, v136, v88
	v_fma_f32 v129, v105, v137, v89
	v_fma_f32 v130, v106, v138, v90
	v_fma_f32 v131, v107, v139, v91
	v_fma_f32 v132, v108, v140, v92
	v_fma_f32 v133, v109, v141, v93
	v_fma_f32 v134, v110, v142, v94
	v_fma_f32 v135, v111, v143, v95
	v_cvt_pk_bf16_f32 v246, v128, v129
	v_cvt_pk_bf16_f32 v247, v130, v131
	v_cvt_pk_bf16_f32 v248, v132, v133
	v_cvt_pk_bf16_f32 v249, v134, v135
	global_store_dwordx4 v5, v[246:249], s[58:59]
	v_add_u32_e32 v5, 0xc00, v5
	v_mul_f32_e32 v136, v128, v112
	v_mul_f32_e32 v137, v129, v113
	v_mul_f32_e32 v138, v130, v114
	v_mul_f32_e32 v139, v131, v115
	v_mul_f32_e32 v140, v132, v116
	v_mul_f32_e32 v141, v133, v117
	v_mul_f32_e32 v142, v134, v118
	v_mul_f32_e32 v143, v135, v119
	v_mul_f32_e32 v144, v136, v136
	v_fmac_f32_e32 v144, v137, v137
	v_fmac_f32_e32 v144, v138, v138
	v_fmac_f32_e32 v144, v139, v139
	v_fmac_f32_e32 v144, v140, v140
	v_fmac_f32_e32 v144, v141, v141
	v_fmac_f32_e32 v144, v142, v142
	v_fmac_f32_e32 v144, v143, v143
	s_nop 1
	v_add_f32_dpp v144, v144, v144 quad_perm:[1,0,3,2] row_mask:0xf bank_mask:0xf bound_ctrl:1
	s_nop 1
	v_add_f32_dpp v144, v144, v144 quad_perm:[2,3,0,1] row_mask:0xf bank_mask:0xf bound_ctrl:1
	s_nop 1
	v_add_f32_dpp v144, v144, v144 row_half_mirror row_mask:0xf bank_mask:0xf bound_ctrl:1
	v_max_f32_e32 v144, 0x179abe15, v144
	v_rsq_f32_e32 v144, v144
	s_mov_b64 s[42:43], exec
	s_and_b64 exec, exec, s[64:65]
	global_store_dword v6, v144, s[58:59]
	s_mov_b64 exec, s[42:43]
	v_add_u32_e32 v6, 32, v6
	v_lshlrev_b32_e32 v80, 16, v192
	v_and_b32_e32 v81, 0xffff0000, v192
	v_lshlrev_b32_e32 v82, 16, v193
	v_and_b32_e32 v83, 0xffff0000, v193
	v_lshlrev_b32_e32 v84, 16, v194
	v_and_b32_e32 v85, 0xffff0000, v194
	v_lshlrev_b32_e32 v86, 16, v195
	v_and_b32_e32 v87, 0xffff0000, v195
	v_add_f32_e32 v136, v88, v80
	v_add_f32_e32 v137, v89, v81
	v_add_f32_e32 v138, v90, v82
	v_add_f32_e32 v139, v91, v83
	v_add_f32_e32 v140, v92, v84
	v_add_f32_e32 v141, v93, v85
	v_add_f32_e32 v142, v94, v86
	v_add_f32_e32 v143, v95, v87
	v_fma_f32 v136, v136, 0.5, -v96
	v_fma_f32 v137, v137, 0.5, -v97
	v_fma_f32 v138, v138, 0.5, -v98
	v_fma_f32 v139, v139, 0.5, -v99
	v_fma_f32 v140, v140, 0.5, -v100
	v_fma_f32 v141, v141, 0.5, -v101
	v_fma_f32 v142, v142, 0.5, -v102
	v_fma_f32 v143, v143, 0.5, -v103
	v_fma_f32 v128, v104, v136, v96
	v_fma_f32 v129, v105, v137, v97
	v_fma_f32 v130, v106, v138, v98
	v_fma_f32 v131, v107, v139, v99
	v_fma_f32 v132, v108, v140, v100
	v_fma_f32 v133, v109, v141, v101
	v_fma_f32 v134, v110, v142, v102
	v_fma_f32 v135, v111, v143, v103
	v_cvt_pk_bf16_f32 v246, v128, v129
	v_cvt_pk_bf16_f32 v247, v130, v131
	v_cvt_pk_bf16_f32 v248, v132, v133
	v_cvt_pk_bf16_f32 v249, v134, v135
	global_store_dwordx4 v5, v[246:249], s[58:59]
	v_add_u32_e32 v5, 0xc00, v5
	v_mul_f32_e32 v136, v128, v112
	v_mul_f32_e32 v137, v129, v113
	v_mul_f32_e32 v138, v130, v114
	v_mul_f32_e32 v139, v131, v115
	v_mul_f32_e32 v140, v132, v116
	v_mul_f32_e32 v141, v133, v117
	v_mul_f32_e32 v142, v134, v118
; __device__ __forceinline__ void unpack8(const u32x4 w, float (&f)[8]) { f[0] = bflo(w.x); f[1] = bfhi(w.x); f[2] = bflo(w.y); f[3] = bfhi(w.y); f[4] = bflo(w.z); f[5] = bfhi(w.z); f[6] = bflo(w.w); f[7] = bfhi(w.w); }
; __device__ __forceinline__ u32x4 pack8(const float (&f)[8]) { u32x4 o; o.x = pk2(f[0], f[1]); o.y = pk2(f[2], f[3]); o.z = pk2(f[4], f[5]); o.w = pk2(f[6], f[7]); return o; }
; template <int CH> __device__ __forceinline__ void p2_rwkv_chunk(const Params& p, int t0, int lane) {
;     ...
;     for (int i = 0; i < 16; ++i) {
;         const int t = t0 + i; const bool hasn = (t & (T_SEQ - 1)) != T_SEQ - 1;
;         if (hasn) unpack8(raw, N); else {
; #pragma unroll
;             for (int q = 0; q < 8; ++q) N[q] = 0.f; }
;         if (i < 15 && ((t + 1) & (T_SEQ - 1)) != T_SEQ - 1) raw = __builtin_nontemporal_load((const u32x4*)(zc + (size_t)(i + 2) * ZLD));
;         float zs[8];
; #pragma unroll
;         for (int q = 0; q < 8; ++q) zs[q] = C[q] + mu[q] * (0.5f * (P[q] + N[q]) - C[q]);
;         if (CH < 3) {
;             *(u32x4*)(RKV + (size_t)t * 1536 + c) = pack8(zs);
;             if (CH == 1) { float s2 = 0.f;
; #pragma unroll
;                 for (int q = 0; q < 8; ++q) { const float v = zs[q] * kq[q]; s2 += v * v; }
;                 s2 = red8s(s2);
;                 if ((lane & 7) == 0) RINV[t * 8 + (lane >> 3)] = rsqrtf(fmaxf(s2, 1e-24f)); }
	v_mul_f32_e32 v143, v135, v119
	v_mul_f32_e32 v144, v136, v136
	v_fmac_f32_e32 v144, v137, v137
	v_fmac_f32_e32 v144, v138, v138
	v_fmac_f32_e32 v144, v139, v139
	v_fmac_f32_e32 v144, v140, v140
	v_fmac_f32_e32 v144, v141, v141
	v_fmac_f32_e32 v144, v142, v142
	v_fmac_f32_e32 v144, v143, v143
	s_nop 1
	v_add_f32_dpp v144, v144, v144 quad_perm:[1,0,3,2] row_mask:0xf bank_mask:0xf bound_ctrl:1
	s_nop 1
	v_add_f32_dpp v144, v144, v144 quad_perm:[2,3,0,1] row_mask:0xf bank_mask:0xf bound_ctrl:1
	s_nop 1
	v_add_f32_dpp v144, v144, v144 row_half_mirror row_mask:0xf bank_mask:0xf bound_ctrl:1
	v_max_f32_e32 v144, 0x179abe15, v144
	v_rsq_f32_e32 v144, v144
	s_mov_b64 s[42:43], exec
	s_and_b64 exec, exec, s[64:65]
	global_store_dword v6, v144, s[58:59]
	s_mov_b64 exec, s[42:43]
	v_add_u32_e32 v6, 32, v6
	v_lshlrev_b32_e32 v88, 16, v196
	v_and_b32_e32 v89, 0xffff0000, v196
	v_lshlrev_b32_e32 v90, 16, v197
	v_and_b32_e32 v91, 0xffff0000, v197
	v_lshlrev_b32_e32 v92, 16, v198
	v_and_b32_e32 v93, 0xffff0000, v198
	v_lshlrev_b32_e32 v94, 16, v199
	v_and_b32_e32 v95, 0xffff0000, v199
	v_add_f32_e32 v136, v96, v88
	v_add_f32_e32 v137, v97, v89
	v_add_f32_e32 v138, v98, v90
	v_add_f32_e32 v139, v99, v91
	v_add_f32_e32 v140, v100, v92
	v_add_f32_e32 v141, v101, v93
	v_add_f32_e32 v142, v102, v94
	v_add_f32_e32 v143, v103, v95
	v_fma_f32 v136, v136, 0.5, -v80
	v_fma_f32 v137, v137, 0.5, -v81
	v_fma_f32 v138, v138, 0.5, -v82
	v_fma_f32 v139, v139, 0.5, -v83
	v_fma_f32 v140, v140, 0.5, -v84
	v_fma_f32 v141, v141, 0.5, -v85
	v_fma_f32 v142, v142, 0.5, -v86
	v_fma_f32 v143, v143, 0.5, -v87
	v_fma_f32 v128, v104, v136, v80
	v_fma_f32 v129, v105, v137, v81
	v_fma_f32 v130, v106, v138, v82
	v_fma_f32 v131, v107, v139, v83
	v_fma_f32 v132, v108, v140, v84
	v_fma_f32 v133, v109, v141, v85
	v_fma_f32 v134, v110, v142, v86
	v_fma_f32 v135, v111, v143, v87
	v_cvt_pk_bf16_f32 v246, v128, v129
	v_cvt_pk_bf16_f32 v247, v130, v131
	v_cvt_pk_bf16_f32 v248, v132, v133
	v_cvt_pk_bf16_f32 v249, v134, v135
	global_store_dwordx4 v5, v[246:249], s[58:59]
	v_add_u32_e32 v5, 0xc00, v5
	v_mul_f32_e32 v136, v128, v112
	v_mul_f32_e32 v137, v129, v113
	v_mul_f32_e32 v138, v130, v114
	v_mul_f32_e32 v139, v131, v115
	v_mul_f32_e32 v140, v132, v116
	v_mul_f32_e32 v141, v133, v117
	v_mul_f32_e32 v142, v134, v118
	v_mul_f32_e32 v143, v135, v119
	v_mul_f32_e32 v144, v136, v136
	v_fmac_f32_e32 v144, v137, v137
	v_fmac_f32_e32 v144, v138, v138
	v_fmac_f32_e32 v144, v139, v139
	v_fmac_f32_e32 v144, v140, v140
	v_fmac_f32_e32 v144, v141, v141
	v_fmac_f32_e32 v144, v142, v142
	v_fmac_f32_e32 v144, v143, v143
	s_nop 1
	v_add_f32_dpp v144, v144, v144 quad_perm:[1,0,3,2] row_mask:0xf bank_mask:0xf bound_ctrl:1
	s_nop 1
	v_add_f32_dpp v144, v144, v144 quad_perm:[2,3,0,1] row_mask:0xf bank_mask:0xf bound_ctrl:1
	s_nop 1
	v_add_f32_dpp v144, v144, v144 row_half_mirror row_mask:0xf bank_mask:0xf bound_ctrl:1
	v_max_f32_e32 v144, 0x179abe15, v144
	v_rsq_f32_e32 v144, v144
	s_mov_b64 s[42:43], exec
	s_and_b64 exec, exec, s[64:65]
	global_store_dword v6, v144, s[58:59]
	s_mov_b64 exec, s[42:43]
	v_add_u32_e32 v6, 32, v6
	v_lshlrev_b32_e32 v96, 16, v200
	v_and_b32_e32 v97, 0xffff0000, v200
	v_lshlrev_b32_e32 v98, 16, v201
	v_and_b32_e32 v99, 0xffff0000, v201
	v_lshlrev_b32_e32 v100, 16, v202
	v_and_b32_e32 v101, 0xffff0000, v202
	v_lshlrev_b32_e32 v102, 16, v203
	v_and_b32_e32 v103, 0xffff0000, v203
	v_add_f32_e32 v136, v80, v96
	v_add_f32_e32 v137, v81, v97
	v_add_f32_e32 v138, v82, v98
	v_add_f32_e32 v139, v83, v99
	v_add_f32_e32 v140, v84, v100
	v_add_f32_e32 v141, v85, v101
	v_add_f32_e32 v142, v86, v102
	v_add_f32_e32 v143, v87, v103
	v_fma_f32 v136, v136, 0.5, -v88
	v_fma_f32 v137, v137, 0.5, -v89
	v_fma_f32 v138, v138, 0.5, -v90
	v_fma_f32 v139, v139, 0.5, -v91
	v_fma_f32 v140, v140, 0.5, -v92
	v_fma_f32 v141, v141, 0.5, -v93
	v_fma_f32 v142, v142, 0.5, -v94
	v_fma_f32 v143, v143, 0.5, -v95
	v_fma_f32 v128, v104, v136, v88
	v_fma_f32 v129, v105, v137, v89
	v_fma_f32 v130, v106, v138, v90
	v_fma_f32 v131, v107, v139, v91
	v_fma_f32 v132, v108, v140, v92
	v_fma_f32 v133, v109, v141, v93
	v_fma_f32 v134, v110, v142, v94
	v_fma_f32 v135, v111, v143, v95
	v_cvt_pk_bf16_f32 v246, v128, v129
	v_cvt_pk_bf16_f32 v247, v130, v131
	v_cvt_pk_bf16_f32 v248, v132, v133
	v_cvt_pk_bf16_f32 v249, v134, v135
	global_store_dwordx4 v5, v[246:249], s[58:59]
	v_add_u32_e32 v5, 0xc00, v5
	v_mul_f32_e32 v136, v128, v112
	v_mul_f32_e32 v137, v129, v113
	v_mul_f32_e32 v138, v130, v114
	v_mul_f32_e32 v139, v131, v115
	v_mul_f32_e32 v140, v132, v116
	v_mul_f32_e32 v141, v133, v117
	v_mul_f32_e32 v142, v134, v118
	v_mul_f32_e32 v143, v135, v119
	v_mul_f32_e32 v144, v136, v136
	v_fmac_f32_e32 v144, v137, v137
	v_fmac_f32_e32 v144, v138, v138
	v_fmac_f32_e32 v144, v139, v139
	v_fmac_f32_e32 v144, v140, v140
	v_fmac_f32_e32 v144, v141, v141
	v_fmac_f32_e32 v144, v142, v142
	v_fmac_f32_e32 v144, v143, v143
	s_nop 1
	v_add_f32_dpp v144, v144, v144 quad_perm:[1,0,3,2] row_mask:0xf bank_mask:0xf bound_ctrl:1
	s_nop 1
	v_add_f32_dpp v144, v144, v144 quad_perm:[2,3,0,1] row_mask:0xf bank_mask:0xf bound_ctrl:1
	s_nop 1
	v_add_f32_dpp v144, v144, v144 row_half_mirror row_mask:0xf bank_mask:0xf bound_ctrl:1
	v_max_f32_e32 v144, 0x179abe15, v144
	v_rsq_f32_e32 v144, v144
	s_mov_b64 s[42:43], exec
	s_and_b64 exec, exec, s[64:65]
	global_store_dword v6, v144, s[58:59]
	s_mov_b64 exec, s[42:43]
	v_add_u32_e32 v6, 32, v6
	v_lshlrev_b32_e32 v80, 16, v204
	v_and_b32_e32 v81, 0xffff0000, v204
	v_lshlrev_b32_e32 v82, 16, v205
	v_and_b32_e32 v83, 0xffff0000, v205
	v_lshlrev_b32_e32 v84, 16, v206
	v_and_b32_e32 v85, 0xffff0000, v206
; __device__ __forceinline__ void unpack8(const u32x4 w, float (&f)[8]) { f[0] = bflo(w.x); f[1] = bfhi(w.x); f[2] = bflo(w.y); f[3] = bfhi(w.y); f[4] = bflo(w.z); f[5] = bfhi(w.z); f[6] = bflo(w.w); f[7] = bfhi(w.w); }
; __device__ __forceinline__ u32x4 pack8(const float (&f)[8]) { u32x4 o; o.x = pk2(f[0], f[1]); o.y = pk2(f[2], f[3]); o.z = pk2(f[4], f[5]); o.w = pk2(f[6], f[7]); return o; }
; template <int CH> __device__ __forceinline__ void p2_rwkv_chunk(const Params& p, int t0, int lane) {
;     ...
;     for (int i = 0; i < 16; ++i) {
;         const int t = t0 + i; const bool hasn = (t & (T_SEQ - 1)) != T_SEQ - 1;
;         if (hasn) unpack8(raw, N); else {
; #pragma unroll
;             for (int q = 0; q < 8; ++q) N[q] = 0.f; }
;         if (i < 15 && ((t + 1) & (T_SEQ - 1)) != T_SEQ - 1) raw = __builtin_nontemporal_load((const u32x4*)(zc + (size_t)(i + 2) * ZLD));
;         float zs[8];
; #pragma unroll
;         for (int q = 0; q < 8; ++q) zs[q] = C[q] + mu[q] * (0.5f * (P[q] + N[q]) - C[q]);
;         if (CH < 3) {
;             *(u32x4*)(RKV + (size_t)t * 1536 + c) = pack8(zs);
;             if (CH == 1) { float s2 = 0.f;
; #pragma unroll
;                 for (int q = 0; q < 8; ++q) { const float v = zs[q] * kq[q]; s2 += v * v; }
;                 s2 = red8s(s2);
;                 if ((lane & 7) == 0) RINV[t * 8 + (lane >> 3)] = rsqrtf(fmaxf(s2, 1e-24f)); }
	v_lshlrev_b32_e32 v86, 16, v207
	v_and_b32_e32 v87, 0xffff0000, v207
	v_add_f32_e32 v136, v88, v80
	v_add_f32_e32 v137, v89, v81
	v_add_f32_e32 v138, v90, v82
	v_add_f32_e32 v139, v91, v83
	v_add_f32_e32 v140, v92, v84
	v_add_f32_e32 v141, v93, v85
	v_add_f32_e32 v142, v94, v86
	v_add_f32_e32 v143, v95, v87
	v_fma_f32 v136, v136, 0.5, -v96
	v_fma_f32 v137, v137, 0.5, -v97
	v_fma_f32 v138, v138, 0.5, -v98
	v_fma_f32 v139, v139, 0.5, -v99
	v_fma_f32 v140, v140, 0.5, -v100
	v_fma_f32 v141, v141, 0.5, -v101
	v_fma_f32 v142, v142, 0.5, -v102
	v_fma_f32 v143, v143, 0.5, -v103
	v_fma_f32 v128, v104, v136, v96
	v_fma_f32 v129, v105, v137, v97
	v_fma_f32 v130, v106, v138, v98
	v_fma_f32 v131, v107, v139, v99
	v_fma_f32 v132, v108, v140, v100
	v_fma_f32 v133, v109, v141, v101
	v_fma_f32 v134, v110, v142, v102
	v_fma_f32 v135, v111, v143, v103
	v_cvt_pk_bf16_f32 v246, v128, v129
	v_cvt_pk_bf16_f32 v247, v130, v131
	v_cvt_pk_bf16_f32 v248, v132, v133
	v_cvt_pk_bf16_f32 v249, v134, v135
	global_store_dwordx4 v5, v[246:249], s[58:59]
	v_add_u32_e32 v5, 0xc00, v5
	v_mul_f32_e32 v136, v128, v112
	v_mul_f32_e32 v137, v129, v113
	v_mul_f32_e32 v138, v130, v114
	v_mul_f32_e32 v139, v131, v115
	v_mul_f32_e32 v140, v132, v116
	v_mul_f32_e32 v141, v133, v117
	v_mul_f32_e32 v142, v134, v118
	v_mul_f32_e32 v143, v135, v119
	v_mul_f32_e32 v144, v136, v136
	v_fmac_f32_e32 v144, v137, v137
	v_fmac_f32_e32 v144, v138, v138
	v_fmac_f32_e32 v144, v139, v139
	v_fmac_f32_e32 v144, v140, v140
	v_fmac_f32_e32 v144, v141, v141
	v_fmac_f32_e32 v144, v142, v142
	v_fmac_f32_e32 v144, v143, v143
	s_nop 1
	v_add_f32_dpp v144, v144, v144 quad_perm:[1,0,3,2] row_mask:0xf bank_mask:0xf bound_ctrl:1
	s_nop 1
	v_add_f32_dpp v144, v144, v144 quad_perm:[2,3,0,1] row_mask:0xf bank_mask:0xf bound_ctrl:1
	s_nop 1
	v_add_f32_dpp v144, v144, v144 row_half_mirror row_mask:0xf bank_mask:0xf bound_ctrl:1
	v_max_f32_e32 v144, 0x179abe15, v144
	v_rsq_f32_e32 v144, v144
	s_mov_b64 s[42:43], exec
	s_and_b64 exec, exec, s[64:65]
	global_store_dword v6, v144, s[58:59]
	s_mov_b64 exec, s[42:43]
	v_add_u32_e32 v6, 32, v6
	v_lshlrev_b32_e32 v88, 16, v208
	v_and_b32_e32 v89, 0xffff0000, v208
	v_lshlrev_b32_e32 v90, 16, v209
	v_and_b32_e32 v91, 0xffff0000, v209
	v_lshlrev_b32_e32 v92, 16, v210
	v_and_b32_e32 v93, 0xffff0000, v210
	v_lshlrev_b32_e32 v94, 16, v211
	v_and_b32_e32 v95, 0xffff0000, v211
	v_add_f32_e32 v136, v96, v88
	v_add_f32_e32 v137, v97, v89
	v_add_f32_e32 v138, v98, v90
	v_add_f32_e32 v139, v99, v91
	v_add_f32_e32 v140, v100, v92
	v_add_f32_e32 v141, v101, v93
	v_add_f32_e32 v142, v102, v94
	v_add_f32_e32 v143, v103, v95
	v_fma_f32 v136, v136, 0.5, -v80
	v_fma_f32 v137, v137, 0.5, -v81
	v_fma_f32 v138, v138, 0.5, -v82
	v_fma_f32 v139, v139, 0.5, -v83
	v_fma_f32 v140, v140, 0.5, -v84
	v_fma_f32 v141, v141, 0.5, -v85
	v_fma_f32 v142, v142, 0.5, -v86
	v_fma_f32 v143, v143, 0.5, -v87
	v_fma_f32 v128, v104, v136, v80
	v_fma_f32 v129, v105, v137, v81
	v_fma_f32 v130, v106, v138, v82
	v_fma_f32 v131, v107, v139, v83
	v_fma_f32 v132, v108, v140, v84
	v_fma_f32 v133, v109, v141, v85
	v_fma_f32 v134, v110, v142, v86
	v_fma_f32 v135, v111, v143, v87
	v_cvt_pk_bf16_f32 v246, v128, v129
	v_cvt_pk_bf16_f32 v247, v130, v131
	v_cvt_pk_bf16_f32 v248, v132, v133
	v_cvt_pk_bf16_f32 v249, v134, v135
	global_store_dwordx4 v5, v[246:249], s[58:59]
	v_add_u32_e32 v5, 0xc00, v5
	v_mul_f32_e32 v136, v128, v112
	v_mul_f32_e32 v137, v129, v113
	v_mul_f32_e32 v138, v130, v114
	v_mul_f32_e32 v139, v131, v115
	v_mul_f32_e32 v140, v132, v116
	v_mul_f32_e32 v141, v133, v117
	v_mul_f32_e32 v142, v134, v118
	v_mul_f32_e32 v143, v135, v119
	v_mul_f32_e32 v144, v136, v136
	v_fmac_f32_e32 v144, v137, v137
	v_fmac_f32_e32 v144, v138, v138
	v_fmac_f32_e32 v144, v139, v139
	v_fmac_f32_e32 v144, v140, v140
	v_fmac_f32_e32 v144, v141, v141
	v_fmac_f32_e32 v144, v142, v142
	v_fmac_f32_e32 v144, v143, v143
	s_nop 1
	v_add_f32_dpp v144, v144, v144 quad_perm:[1,0,3,2] row_mask:0xf bank_mask:0xf bound_ctrl:1
	s_nop 1
	v_add_f32_dpp v144, v144, v144 quad_perm:[2,3,0,1] row_mask:0xf bank_mask:0xf bound_ctrl:1
	s_nop 1
	v_add_f32_dpp v144, v144, v144 row_half_mirror row_mask:0xf bank_mask:0xf bound_ctrl:1
	v_max_f32_e32 v144, 0x179abe15, v144
	v_rsq_f32_e32 v144, v144
	s_mov_b64 s[42:43], exec
	s_and_b64 exec, exec, s[64:65]
	global_store_dword v6, v144, s[58:59]
	s_mov_b64 exec, s[42:43]
	v_add_u32_e32 v6, 32, v6
	v_lshlrev_b32_e32 v96, 16, v212
	v_and_b32_e32 v97, 0xffff0000, v212
	v_lshlrev_b32_e32 v98, 16, v213
	v_and_b32_e32 v99, 0xffff0000, v213
	v_lshlrev_b32_e32 v100, 16, v214
	v_and_b32_e32 v101, 0xffff0000, v214
	v_lshlrev_b32_e32 v102, 16, v215
	v_and_b32_e32 v103, 0xffff0000, v215
	v_add_f32_e32 v136, v80, v96
	v_add_f32_e32 v137, v81, v97
	v_add_f32_e32 v138, v82, v98
	v_add_f32_e32 v139, v83, v99
	v_add_f32_e32 v140, v84, v100
	v_add_f32_e32 v141, v85, v101
	v_add_f32_e32 v142, v86, v102
	v_add_f32_e32 v143, v87, v103
	v_fma_f32 v136, v136, 0.5, -v88
	v_fma_f32 v137, v137, 0.5, -v89
	v_fma_f32 v138, v138, 0.5, -v90
	v_fma_f32 v139, v139, 0.5, -v91
	v_fma_f32 v140, v140, 0.5, -v92
	v_fma_f32 v141, v141, 0.5, -v93
	v_fma_f32 v142, v142, 0.5, -v94
	v_fma_f32 v143, v143, 0.5, -v95
	v_fma_f32 v128, v104, v136, v88
	v_fma_f32 v129, v105, v137, v89
	v_fma_f32 v130, v106, v138, v90
	v_fma_f32 v131, v107, v139, v91
	v_fma_f32 v132, v108, v140, v92
	v_fma_f32 v133, v109, v141, v93
	v_fma_f32 v134, v110, v142, v94
	v_fma_f32 v135, v111, v143, v95
	v_cvt_pk_bf16_f32 v246, v128, v129
	v_cvt_pk_bf16_f32 v247, v130, v131
	v_cvt_pk_bf16_f32 v248, v132, v133
	v_cvt_pk_bf16_f32 v249, v134, v135
	global_store_dwordx4 v5, v[246:249], s[58:59]
; __device__ __forceinline__ void unpack8(const u32x4 w, float (&f)[8]) { f[0] = bflo(w.x); f[1] = bfhi(w.x); f[2] = bflo(w.y); f[3] = bfhi(w.y); f[4] = bflo(w.z); f[5] = bfhi(w.z); f[6] = bflo(w.w); f[7] = bfhi(w.w); }
; __device__ __forceinline__ u32x4 pack8(const float (&f)[8]) { u32x4 o; o.x = pk2(f[0], f[1]); o.y = pk2(f[2], f[3]); o.z = pk2(f[4], f[5]); o.w = pk2(f[6], f[7]); return o; }
; template <int CH> __device__ __forceinline__ void p2_rwkv_chunk(const Params& p, int t0, int lane) {
;     ...
;     for (int i = 0; i < 16; ++i) {
;         const int t = t0 + i; const bool hasn = (t & (T_SEQ - 1)) != T_SEQ - 1;
;         if (hasn) unpack8(raw, N); else {
; #pragma unroll
;             for (int q = 0; q < 8; ++q) N[q] = 0.f; }
;         if (i < 15 && ((t + 1) & (T_SEQ - 1)) != T_SEQ - 1) raw = __builtin_nontemporal_load((const u32x4*)(zc + (size_t)(i + 2) * ZLD));
;         float zs[8];
; #pragma unroll
;         for (int q = 0; q < 8; ++q) zs[q] = C[q] + mu[q] * (0.5f * (P[q] + N[q]) - C[q]);
;         if (CH < 3) {
;             *(u32x4*)(RKV + (size_t)t * 1536 + c) = pack8(zs);
;             if (CH == 1) { float s2 = 0.f;
; #pragma unroll
;                 for (int q = 0; q < 8; ++q) { const float v = zs[q] * kq[q]; s2 += v * v; }
;                 s2 = red8s(s2);
;                 if ((lane & 7) == 0) RINV[t * 8 + (lane >> 3)] = rsqrtf(fmaxf(s2, 1e-24f)); }
	v_add_u32_e32 v5, 0xc00, v5
	v_mul_f32_e32 v136, v128, v112
	v_mul_f32_e32 v137, v129, v113
	v_mul_f32_e32 v138, v130, v114
	v_mul_f32_e32 v139, v131, v115
	v_mul_f32_e32 v140, v132, v116
	v_mul_f32_e32 v141, v133, v117
	v_mul_f32_e32 v142, v134, v118
	v_mul_f32_e32 v143, v135, v119
	v_mul_f32_e32 v144, v136, v136
	v_fmac_f32_e32 v144, v137, v137
	v_fmac_f32_e32 v144, v138, v138
	v_fmac_f32_e32 v144, v139, v139
	v_fmac_f32_e32 v144, v140, v140
	v_fmac_f32_e32 v144, v141, v141
	v_fmac_f32_e32 v144, v142, v142
	v_fmac_f32_e32 v144, v143, v143
	s_nop 1
	v_add_f32_dpp v144, v144, v144 quad_perm:[1,0,3,2] row_mask:0xf bank_mask:0xf bound_ctrl:1
	s_nop 1
	v_add_f32_dpp v144, v144, v144 quad_perm:[2,3,0,1] row_mask:0xf bank_mask:0xf bound_ctrl:1
	s_nop 1
	v_add_f32_dpp v144, v144, v144 row_half_mirror row_mask:0xf bank_mask:0xf bound_ctrl:1
	v_max_f32_e32 v144, 0x179abe15, v144
	v_rsq_f32_e32 v144, v144
	s_mov_b64 s[42:43], exec
	s_and_b64 exec, exec, s[64:65]
	global_store_dword v6, v144, s[58:59]
	s_mov_b64 exec, s[42:43]
	v_add_u32_e32 v6, 32, v6
	v_lshlrev_b32_e32 v80, 16, v216
	v_and_b32_e32 v81, 0xffff0000, v216
	v_lshlrev_b32_e32 v82, 16, v217
	v_and_b32_e32 v83, 0xffff0000, v217
	v_lshlrev_b32_e32 v84, 16, v218
	v_and_b32_e32 v85, 0xffff0000, v218
	v_lshlrev_b32_e32 v86, 16, v219
	v_and_b32_e32 v87, 0xffff0000, v219
	v_add_f32_e32 v136, v88, v80
	v_add_f32_e32 v137, v89, v81
	v_add_f32_e32 v138, v90, v82
	v_add_f32_e32 v139, v91, v83
	v_add_f32_e32 v140, v92, v84
	v_add_f32_e32 v141, v93, v85
	v_add_f32_e32 v142, v94, v86
	v_add_f32_e32 v143, v95, v87
	v_fma_f32 v136, v136, 0.5, -v96
	v_fma_f32 v137, v137, 0.5, -v97
	v_fma_f32 v138, v138, 0.5, -v98
	v_fma_f32 v139, v139, 0.5, -v99
	v_fma_f32 v140, v140, 0.5, -v100
	v_fma_f32 v141, v141, 0.5, -v101
	v_fma_f32 v142, v142, 0.5, -v102
	v_fma_f32 v143, v143, 0.5, -v103
	v_fma_f32 v128, v104, v136, v96
	v_fma_f32 v129, v105, v137, v97
	v_fma_f32 v130, v106, v138, v98
	v_fma_f32 v131, v107, v139, v99
	v_fma_f32 v132, v108, v140, v100
	v_fma_f32 v133, v109, v141, v101
	v_fma_f32 v134, v110, v142, v102
	v_fma_f32 v135, v111, v143, v103
	v_cvt_pk_bf16_f32 v246, v128, v129
	v_cvt_pk_bf16_f32 v247, v130, v131
	v_cvt_pk_bf16_f32 v248, v132, v133
	v_cvt_pk_bf16_f32 v249, v134, v135
	global_store_dwordx4 v5, v[246:249], s[58:59]
	v_add_u32_e32 v5, 0xc00, v5
	v_mul_f32_e32 v136, v128, v112
	v_mul_f32_e32 v137, v129, v113
	v_mul_f32_e32 v138, v130, v114
	v_mul_f32_e32 v139, v131, v115
	v_mul_f32_e32 v140, v132, v116
	v_mul_f32_e32 v141, v133, v117
	v_mul_f32_e32 v142, v134, v118
	v_mul_f32_e32 v143, v135, v119
	v_mul_f32_e32 v144, v136, v136
	v_fmac_f32_e32 v144, v137, v137
	v_fmac_f32_e32 v144, v138, v138
	v_fmac_f32_e32 v144, v139, v139
	v_fmac_f32_e32 v144, v140, v140
	v_fmac_f32_e32 v144, v141, v141
	v_fmac_f32_e32 v144, v142, v142
	v_fmac_f32_e32 v144, v143, v143
	s_nop 1
	v_add_f32_dpp v144, v144, v144 quad_perm:[1,0,3,2] row_mask:0xf bank_mask:0xf bound_ctrl:1
	s_nop 1
	v_add_f32_dpp v144, v144, v144 quad_perm:[2,3,0,1] row_mask:0xf bank_mask:0xf bound_ctrl:1
	s_nop 1
	v_add_f32_dpp v144, v144, v144 row_half_mirror row_mask:0xf bank_mask:0xf bound_ctrl:1
	v_max_f32_e32 v144, 0x179abe15, v144
	v_rsq_f32_e32 v144, v144
	s_mov_b64 s[42:43], exec
	s_and_b64 exec, exec, s[64:65]
	global_store_dword v6, v144, s[58:59]
	s_mov_b64 exec, s[42:43]
	v_add_u32_e32 v6, 32, v6
	v_lshlrev_b32_e32 v88, 16, v220
	v_and_b32_e32 v89, 0xffff0000, v220
	v_lshlrev_b32_e32 v90, 16, v221
	v_and_b32_e32 v91, 0xffff0000, v221
	v_lshlrev_b32_e32 v92, 16, v222
	v_and_b32_e32 v93, 0xffff0000, v222
	v_lshlrev_b32_e32 v94, 16, v223
	v_and_b32_e32 v95, 0xffff0000, v223
	v_add_f32_e32 v136, v96, v88
	v_add_f32_e32 v137, v97, v89
	v_add_f32_e32 v138, v98, v90
	v_add_f32_e32 v139, v99, v91
	v_add_f32_e32 v140, v100, v92
	v_add_f32_e32 v141, v101, v93
	v_add_f32_e32 v142, v102, v94
	v_add_f32_e32 v143, v103, v95
	v_fma_f32 v136, v136, 0.5, -v80
	v_fma_f32 v137, v137, 0.5, -v81
	v_fma_f32 v138, v138, 0.5, -v82
	v_fma_f32 v139, v139, 0.5, -v83
	v_fma_f32 v140, v140, 0.5, -v84
	v_fma_f32 v141, v141, 0.5, -v85
	v_fma_f32 v142, v142, 0.5, -v86
	v_fma_f32 v143, v143, 0.5, -v87
	v_fma_f32 v128, v104, v136, v80
	v_fma_f32 v129, v105, v137, v81
	v_fma_f32 v130, v106, v138, v82
	v_fma_f32 v131, v107, v139, v83
	v_fma_f32 v132, v108, v140, v84
	v_fma_f32 v133, v109, v141, v85
	v_fma_f32 v134, v110, v142, v86
	v_fma_f32 v135, v111, v143, v87
	v_cvt_pk_bf16_f32 v246, v128, v129
	v_cvt_pk_bf16_f32 v247, v130, v131
	v_cvt_pk_bf16_f32 v248, v132, v133
	v_cvt_pk_bf16_f32 v249, v134, v135
	global_store_dwordx4 v5, v[246:249], s[58:59]
	v_add_u32_e32 v5, 0xc00, v5
	v_mul_f32_e32 v136, v128, v112
	v_mul_f32_e32 v137, v129, v113
	v_mul_f32_e32 v138, v130, v114
	v_mul_f32_e32 v139, v131, v115
	v_mul_f32_e32 v140, v132, v116
	v_mul_f32_e32 v141, v133, v117
	v_mul_f32_e32 v142, v134, v118
	v_mul_f32_e32 v143, v135, v119
	v_mul_f32_e32 v144, v136, v136
	v_fmac_f32_e32 v144, v137, v137
	v_fmac_f32_e32 v144, v138, v138
	v_fmac_f32_e32 v144, v139, v139
	v_fmac_f32_e32 v144, v140, v140
	v_fmac_f32_e32 v144, v141, v141
	v_fmac_f32_e32 v144, v142, v142
	v_fmac_f32_e32 v144, v143, v143
	s_nop 1
	v_add_f32_dpp v144, v144, v144 quad_perm:[1,0,3,2] row_mask:0xf bank_mask:0xf bound_ctrl:1
	s_nop 1
	v_add_f32_dpp v144, v144, v144 quad_perm:[2,3,0,1] row_mask:0xf bank_mask:0xf bound_ctrl:1
	s_nop 1
	v_add_f32_dpp v144, v144, v144 row_half_mirror row_mask:0xf bank_mask:0xf bound_ctrl:1
	v_max_f32_e32 v144, 0x179abe15, v144
	v_rsq_f32_e32 v144, v144
	s_mov_b64 s[42:43], exec
	s_and_b64 exec, exec, s[64:65]
	global_store_dword v6, v144, s[58:59]
	s_mov_b64 exec, s[42:43]
; __device__ __forceinline__ u32x4 pack8(const float (&f)[8]) { u32x4 o; o.x = pk2(f[0], f[1]); o.y = pk2(f[2], f[3]); o.z = pk2(f[4], f[5]); o.w = pk2(f[6], f[7]); return o; }
; template <int CH> __device__ __forceinline__ void p2_rwkv_chunk(const Params& p, int t0, int lane) {
;     ...
;         for (int q = 0; q < 8; ++q) zs[q] = C[q] + mu[q] * (0.5f * (P[q] + N[q]) - C[q]);
;         if (CH < 3) {
;             *(u32x4*)(RKV + (size_t)t * 1536 + c) = pack8(zs);
;             if (CH == 1) { float s2 = 0.f;
; #pragma unroll
;                 for (int q = 0; q < 8; ++q) { const float v = zs[q] * kq[q]; s2 += v * v; }
;                 s2 = red8s(s2);
;                 if ((lane & 7) == 0) RINV[t * 8 + (lane >> 3)] = rsqrtf(fmaxf(s2, 1e-24f)); }
	v_add_u32_e32 v6, 32, v6
	v_lshlrev_b32_e32 v96, 16, v224
	v_and_b32_e32 v97, 0xffff0000, v224
	v_lshlrev_b32_e32 v98, 16, v225
	v_and_b32_e32 v99, 0xffff0000, v225
	v_lshlrev_b32_e32 v100, 16, v226
	v_and_b32_e32 v101, 0xffff0000, v226
	v_lshlrev_b32_e32 v102, 16, v227
	v_and_b32_e32 v103, 0xffff0000, v227
	v_add_f32_e32 v136, v80, v96
	v_add_f32_e32 v137, v81, v97
	v_add_f32_e32 v138, v82, v98
	v_add_f32_e32 v139, v83, v99
	v_add_f32_e32 v140, v84, v100
	v_add_f32_e32 v141, v85, v101
	v_add_f32_e32 v142, v86, v102
	v_add_f32_e32 v143, v87, v103
	v_fma_f32 v136, v136, 0.5, -v88
	v_fma_f32 v137, v137, 0.5, -v89
	v_fma_f32 v138, v138, 0.5, -v90
	v_fma_f32 v139, v139, 0.5, -v91
	v_fma_f32 v140, v140, 0.5, -v92
	v_fma_f32 v141, v141, 0.5, -v93
	v_fma_f32 v142, v142, 0.5, -v94
	v_fma_f32 v143, v143, 0.5, -v95
	v_fma_f32 v128, v104, v136, v88
	v_fma_f32 v129, v105, v137, v89
	v_fma_f32 v130, v106, v138, v90
	v_fma_f32 v131, v107, v139, v91
	v_fma_f32 v132, v108, v140, v92
	v_fma_f32 v133, v109, v141, v93
	v_fma_f32 v134, v110, v142, v94
	v_fma_f32 v135, v111, v143, v95
	v_cvt_pk_bf16_f32 v246, v128, v129
	v_cvt_pk_bf16_f32 v247, v130, v131
	v_cvt_pk_bf16_f32 v248, v132, v133
	v_cvt_pk_bf16_f32 v249, v134, v135
	global_store_dwordx4 v5, v[246:249], s[58:59]
	v_add_u32_e32 v5, 0xc00, v5
	v_mul_f32_e32 v136, v128, v112
	v_mul_f32_e32 v137, v129, v113
	v_mul_f32_e32 v138, v130, v114
	v_mul_f32_e32 v139, v131, v115
	v_mul_f32_e32 v140, v132, v116
	v_mul_f32_e32 v141, v133, v117
	v_mul_f32_e32 v142, v134, v118
	v_mul_f32_e32 v143, v135, v119
	v_mul_f32_e32 v144, v136, v136
	v_fmac_f32_e32 v144, v137, v137
	v_fmac_f32_e32 v144, v138, v138
	v_fmac_f32_e32 v144, v139, v139
	v_fmac_f32_e32 v144, v140, v140
	v_fmac_f32_e32 v144, v141, v141
	v_fmac_f32_e32 v144, v142, v142
	v_fmac_f32_e32 v144, v143, v143
	s_nop 1
	v_add_f32_dpp v144, v144, v144 quad_perm:[1,0,3,2] row_mask:0xf bank_mask:0xf bound_ctrl:1
	s_nop 1
	v_add_f32_dpp v144, v144, v144 quad_perm:[2,3,0,1] row_mask:0xf bank_mask:0xf bound_ctrl:1
	s_nop 1
	v_add_f32_dpp v144, v144, v144 row_half_mirror row_mask:0xf bank_mask:0xf bound_ctrl:1
	v_max_f32_e32 v144, 0x179abe15, v144
	v_rsq_f32_e32 v144, v144
	s_mov_b64 s[42:43], exec
	s_and_b64 exec, exec, s[64:65]
	global_store_dword v6, v144, s[58:59]
	s_mov_b64 exec, s[42:43]
	v_add_u32_e32 v6, 32, v6
	v_lshlrev_b32_e32 v80, 16, v228
	v_and_b32_e32 v81, 0xffff0000, v228
	v_lshlrev_b32_e32 v82, 16, v229
	v_and_b32_e32 v83, 0xffff0000, v229
	v_lshlrev_b32_e32 v84, 16, v230
	v_and_b32_e32 v85, 0xffff0000, v230
	v_lshlrev_b32_e32 v86, 16, v231
	v_and_b32_e32 v87, 0xffff0000, v231
	v_add_f32_e32 v136, v88, v80
	v_add_f32_e32 v137, v89, v81
	v_add_f32_e32 v138, v90, v82
	v_add_f32_e32 v139, v91, v83
	v_add_f32_e32 v140, v92, v84
	v_add_f32_e32 v141, v93, v85
	v_add_f32_e32 v142, v94, v86
	v_add_f32_e32 v143, v95, v87
	v_fma_f32 v136, v136, 0.5, -v96
	v_fma_f32 v137, v137, 0.5, -v97
	v_fma_f32 v138, v138, 0.5, -v98
	v_fma_f32 v139, v139, 0.5, -v99
	v_fma_f32 v140, v140, 0.5, -v100
	v_fma_f32 v141, v141, 0.5, -v101
	v_fma_f32 v142, v142, 0.5, -v102
	v_fma_f32 v143, v143, 0.5, -v103
	v_fma_f32 v128, v104, v136, v96
	v_fma_f32 v129, v105, v137, v97
	v_fma_f32 v130, v106, v138, v98
	v_fma_f32 v131, v107, v139, v99
	v_fma_f32 v132, v108, v140, v100
	v_fma_f32 v133, v109, v141, v101
	v_fma_f32 v134, v110, v142, v102
	v_fma_f32 v135, v111, v143, v103
	v_cvt_pk_bf16_f32 v246, v128, v129
	v_cvt_pk_bf16_f32 v247, v130, v131
	v_cvt_pk_bf16_f32 v248, v132, v133
	v_cvt_pk_bf16_f32 v249, v134, v135
	global_store_dwordx4 v5, v[246:249], s[58:59]
	v_add_u32_e32 v5, 0xc00, v5
	v_mul_f32_e32 v136, v128, v112
	v_mul_f32_e32 v137, v129, v113
	v_mul_f32_e32 v138, v130, v114
	v_mul_f32_e32 v139, v131, v115
	v_mul_f32_e32 v140, v132, v116
	v_mul_f32_e32 v141, v133, v117
	v_mul_f32_e32 v142, v134, v118
	v_mul_f32_e32 v143, v135, v119
	v_mul_f32_e32 v144, v136, v136
	v_fmac_f32_e32 v144, v137, v137
	v_fmac_f32_e32 v144, v138, v138
	v_fmac_f32_e32 v144, v139, v139
	v_fmac_f32_e32 v144, v140, v140
	v_fmac_f32_e32 v144, v141, v141
	v_fmac_f32_e32 v144, v142, v142
	v_fmac_f32_e32 v144, v143, v143
	s_nop 1
	v_add_f32_dpp v144, v144, v144 quad_perm:[1,0,3,2] row_mask:0xf bank_mask:0xf bound_ctrl:1
	s_nop 1
	v_add_f32_dpp v144, v144, v144 quad_perm:[2,3,0,1] row_mask:0xf bank_mask:0xf bound_ctrl:1
	s_nop 1
	v_add_f32_dpp v144, v144, v144 row_half_mirror row_mask:0xf bank_mask:0xf bound_ctrl:1
	v_max_f32_e32 v144, 0x179abe15, v144
	v_rsq_f32_e32 v144, v144
	s_mov_b64 s[42:43], exec
	s_and_b64 exec, exec, s[64:65]
	global_store_dword v6, v144, s[58:59]
	s_mov_b64 exec, s[42:43]
	v_add_u32_e32 v6, 32, v6
	v_lshlrev_b32_e32 v88, 16, v232
	v_and_b32_e32 v89, 0xffff0000, v232
	v_lshlrev_b32_e32 v90, 16, v233
	v_and_b32_e32 v91, 0xffff0000, v233
	v_lshlrev_b32_e32 v92, 16, v234
	v_and_b32_e32 v93, 0xffff0000, v234
	v_lshlrev_b32_e32 v94, 16, v235
	v_and_b32_e32 v95, 0xffff0000, v235
	v_add_f32_e32 v136, v96, v88
	v_add_f32_e32 v137, v97, v89
	v_add_f32_e32 v138, v98, v90
	v_add_f32_e32 v139, v99, v91
	v_add_f32_e32 v140, v100, v92
	v_add_f32_e32 v141, v101, v93
	v_add_f32_e32 v142, v102, v94
	v_add_f32_e32 v143, v103, v95
	v_fma_f32 v136, v136, 0.5, -v80
	v_fma_f32 v137, v137, 0.5, -v81
	v_fma_f32 v138, v138, 0.5, -v82
	v_fma_f32 v139, v139, 0.5, -v83
	v_fma_f32 v140, v140, 0.5, -v84
	v_fma_f32 v141, v141, 0.5, -v85
	v_fma_f32 v142, v142, 0.5, -v86
	v_fma_f32 v143, v143, 0.5, -v87
	v_fma_f32 v128, v104, v136, v80
	v_fma_f32 v129, v105, v137, v81
	v_fma_f32 v130, v106, v138, v82
	v_fma_f32 v131, v107, v139, v83
	v_fma_f32 v132, v108, v140, v84
	v_fma_f32 v133, v109, v141, v85
	v_fma_f32 v134, v110, v142, v86
	v_fma_f32 v135, v111, v143, v87
	v_cvt_pk_bf16_f32 v246, v128, v129
	v_cvt_pk_bf16_f32 v247, v130, v131
	v_cvt_pk_bf16_f32 v248, v132, v133
	v_cvt_pk_bf16_f32 v249, v134, v135
	global_store_dwordx4 v5, v[246:249], s[58:59]
	v_add_u32_e32 v5, 0xc00, v5
	v_mul_f32_e32 v136, v128, v112
	v_mul_f32_e32 v137, v129, v113
	v_mul_f32_e32 v138, v130, v114
	v_mul_f32_e32 v139, v131, v115
	v_mul_f32_e32 v140, v132, v116
	v_mul_f32_e32 v141, v133, v117
	v_mul_f32_e32 v142, v134, v118
	v_mul_f32_e32 v143, v135, v119
	v_mul_f32_e32 v144, v136, v136
	v_fmac_f32_e32 v144, v137, v137
	v_fmac_f32_e32 v144, v138, v138
	v_fmac_f32_e32 v144, v139, v139
	v_fmac_f32_e32 v144, v140, v140
	v_fmac_f32_e32 v144, v141, v141
	v_fmac_f32_e32 v144, v142, v142
	v_fmac_f32_e32 v144, v143, v143
	s_nop 1
	v_add_f32_dpp v144, v144, v144 quad_perm:[1,0,3,2] row_mask:0xf bank_mask:0xf bound_ctrl:1
	s_nop 1
	v_add_f32_dpp v144, v144, v144 quad_perm:[2,3,0,1] row_mask:0xf bank_mask:0xf bound_ctrl:1
	s_nop 1
	v_add_f32_dpp v144, v144, v144 row_half_mirror row_mask:0xf bank_mask:0xf bound_ctrl:1
	v_max_f32_e32 v144, 0x179abe15, v144
	v_rsq_f32_e32 v144, v144
	s_mov_b64 s[42:43], exec
	s_and_b64 exec, exec, s[64:65]
	global_store_dword v6, v144, s[58:59]
	s_mov_b64 exec, s[42:43]
	v_add_u32_e32 v6, 32, v6
	s_cmp_eq_u32 s67, 0
	s_cbranch_scc1 .Lp2_nz_6
; __device__ __forceinline__ void unpack8(const u32x4 w, float (&f)[8]) { f[0] = bflo(w.x); f[1] = bfhi(w.x); f[2] = bflo(w.y); f[3] = bfhi(w.y); f[4] = bflo(w.z); f[5] = bfhi(w.z); f[6] = bflo(w.w); f[7] = bfhi(w.w); }
; __device__ __forceinline__ u32x4 pack8(const float (&f)[8]) { u32x4 o; o.x = pk2(f[0], f[1]); o.y = pk2(f[2], f[3]); o.z = pk2(f[4], f[5]); o.w = pk2(f[6], f[7]); return o; }
; template <int CH> __device__ __forceinline__ void p2_rwkv_chunk(const Params& p, int t0, int lane) {
;     ...
;     const bf16_t* zc = (const bf16_t*)(ws + WS_Z) + (size_t)t0 * ZLD + c;
;     float mu[8], kq[8];
;     { const f32x4 m0 = *(const f32x4*)(p.in[8] + c), m1 = *(const f32x4*)(p.in[8] + c + 4);
; #pragma unroll
;       for (int i = 0; i < 4; ++i) { mu[i] = m0[i]; mu[4 + i] = m1[i]; } }
;     if (CH == 1) { const f32x4 q0 = *(const f32x4*)(p.in[14] + c - 512), q1 = *(const f32x4*)(p.in[14] + c - 512 + 4);
; #pragma unroll
;         for (int i = 0; i < 4; ++i) { kq[i] = q0[i]; kq[4 + i] = q1[i]; } }
;     float P[8], C[8], N[8];
;     if ((t0 & (T_SEQ - 1)) != 0) unpack8(__builtin_nontemporal_load((const u32x4*)(zc - ZLD)), P); else {
; #pragma unroll
;         for (int i = 0; i < 8; ++i) P[i] = 0.f; }
;     unpack8(__builtin_nontemporal_load((const u32x4*)(zc)), C);
;     u32x4 raw = __builtin_nontemporal_load((const u32x4*)(zc + ZLD));
;     ...
;         for (int q = 0; q < 8; ++q) zs[q] = C[q] + mu[q] * (0.5f * (P[q] + N[q]) - C[q]);
;         if (CH < 3) {
;             *(u32x4*)(RKV + (size_t)t * 1536 + c) = pack8(zs);
;             if (CH == 1) { float s2 = 0.f;
; #pragma unroll
;                 for (int q = 0; q < 8; ++q) { const float v = zs[q] * kq[q]; s2 += v * v; }
;                 s2 = red8s(s2);
;                 if ((lane & 7) == 0) RINV[t * 8 + (lane >> 3)] = rsqrtf(fmaxf(s2, 1e-24f)); }
	v_mov_b32_e32 v236, 0
	v_mov_b32_e32 v237, 0
	v_mov_b32_e32 v238, 0
	v_mov_b32_e32 v239, 0
.Lp2_nz_6:
	v_lshlrev_b32_e32 v96, 16, v236
	v_and_b32_e32 v97, 0xffff0000, v236
	v_lshlrev_b32_e32 v98, 16, v237
	v_and_b32_e32 v99, 0xffff0000, v237
	v_lshlrev_b32_e32 v100, 16, v238
	v_and_b32_e32 v101, 0xffff0000, v238
	v_lshlrev_b32_e32 v102, 16, v239
	v_and_b32_e32 v103, 0xffff0000, v239
	v_add_f32_e32 v136, v80, v96
	v_add_f32_e32 v137, v81, v97
	v_add_f32_e32 v138, v82, v98
	v_add_f32_e32 v139, v83, v99
	v_add_f32_e32 v140, v84, v100
	v_add_f32_e32 v141, v85, v101
	v_add_f32_e32 v142, v86, v102
	v_add_f32_e32 v143, v87, v103
	v_fma_f32 v136, v136, 0.5, -v88
	v_fma_f32 v137, v137, 0.5, -v89
	v_fma_f32 v138, v138, 0.5, -v90
	v_fma_f32 v139, v139, 0.5, -v91
	v_fma_f32 v140, v140, 0.5, -v92
	v_fma_f32 v141, v141, 0.5, -v93
	v_fma_f32 v142, v142, 0.5, -v94
	v_fma_f32 v143, v143, 0.5, -v95
	v_fma_f32 v128, v104, v136, v88
	v_fma_f32 v129, v105, v137, v89
	v_fma_f32 v130, v106, v138, v90
	v_fma_f32 v131, v107, v139, v91
	v_fma_f32 v132, v108, v140, v92
	v_fma_f32 v133, v109, v141, v93
	v_fma_f32 v134, v110, v142, v94
	v_fma_f32 v135, v111, v143, v95
	v_cvt_pk_bf16_f32 v246, v128, v129
	v_cvt_pk_bf16_f32 v247, v130, v131
	v_cvt_pk_bf16_f32 v248, v132, v133
	v_cvt_pk_bf16_f32 v249, v134, v135
	global_store_dwordx4 v5, v[246:249], s[58:59]
	v_add_u32_e32 v5, 0xc00, v5
	v_mul_f32_e32 v136, v128, v112
	v_mul_f32_e32 v137, v129, v113
	v_mul_f32_e32 v138, v130, v114
	v_mul_f32_e32 v139, v131, v115
	v_mul_f32_e32 v140, v132, v116
	v_mul_f32_e32 v141, v133, v117
	v_mul_f32_e32 v142, v134, v118
	v_mul_f32_e32 v143, v135, v119
	v_mul_f32_e32 v144, v136, v136
	v_fmac_f32_e32 v144, v137, v137
	v_fmac_f32_e32 v144, v138, v138
	v_fmac_f32_e32 v144, v139, v139
	v_fmac_f32_e32 v144, v140, v140
	v_fmac_f32_e32 v144, v141, v141
	v_fmac_f32_e32 v144, v142, v142
	v_fmac_f32_e32 v144, v143, v143
	s_nop 1
	v_add_f32_dpp v144, v144, v144 quad_perm:[1,0,3,2] row_mask:0xf bank_mask:0xf bound_ctrl:1
	s_nop 1
	v_add_f32_dpp v144, v144, v144 quad_perm:[2,3,0,1] row_mask:0xf bank_mask:0xf bound_ctrl:1
	s_nop 1
	v_add_f32_dpp v144, v144, v144 row_half_mirror row_mask:0xf bank_mask:0xf bound_ctrl:1
	v_max_f32_e32 v144, 0x179abe15, v144
	v_rsq_f32_e32 v144, v144
	s_mov_b64 s[42:43], exec
	s_and_b64 exec, exec, s[64:65]
	global_store_dword v6, v144, s[58:59]
	s_mov_b64 exec, s[42:43]
	v_add_u32_e32 v6, 32, v6
	s_mov_b32 s98, 0x1000
	s_mov_b32 s99, 0
	v_lshl_add_u64 v[2:3], v[250:251], 0, s[98:99]
	global_load_dwordx4 v[104:107], v[2:3], off
	global_load_dwordx4 v[108:111], v[2:3], off offset:16
	s_mul_i32 s63, s62, 0x1c00
	s_add_u32 s63, s63, 0x7000c00
	v_lshl_add_u32 v4, v0, 4, s63
	v_add_u32_e32 v1, 0xffffe400, v4
	s_cmp_lg_u32 s66, 0
	s_cselect_b64 vcc, -1, 0
	s_nop 1
	v_cndmask_b32_e32 v1, v1, v4, vcc
	global_load_dwordx4 v[168:171], v1, s[58:59] nt
	global_load_dwordx4 v[172:175], v4, s[58:59] nt
	v_mov_b32_e32 v1, v4
	v_add_u32_e32 v1, 0x1c00, v1
	global_load_dwordx4 v[176:179], v1, s[58:59] nt
	v_add_u32_e32 v1, 0x1c00, v1
	global_load_dwordx4 v[180:183], v1, s[58:59] nt
	v_add_u32_e32 v1, 0x1c00, v1
	global_load_dwordx4 v[184:187], v1, s[58:59] nt
	v_add_u32_e32 v1, 0x1c00, v1
	global_load_dwordx4 v[188:191], v1, s[58:59] nt
	v_add_u32_e32 v1, 0x1c00, v1
	global_load_dwordx4 v[192:195], v1, s[58:59] nt
	v_add_u32_e32 v1, 0x1c00, v1
	global_load_dwordx4 v[196:199], v1, s[58:59] nt
	v_add_u32_e32 v1, 0x1c00, v1
	global_load_dwordx4 v[200:203], v1, s[58:59] nt
	v_add_u32_e32 v1, 0x1c00, v1
	global_load_dwordx4 v[204:207], v1, s[58:59] nt
	v_add_u32_e32 v1, 0x1c00, v1
	global_load_dwordx4 v[208:211], v1, s[58:59] nt
	v_add_u32_e32 v1, 0x1c00, v1
	global_load_dwordx4 v[212:215], v1, s[58:59] nt
	v_add_u32_e32 v1, 0x1c00, v1
	global_load_dwordx4 v[216:219], v1, s[58:59] nt
	v_add_u32_e32 v1, 0x1c00, v1
	global_load_dwordx4 v[220:223], v1, s[58:59] nt
	v_add_u32_e32 v1, 0x1c00, v1
	global_load_dwordx4 v[224:227], v1, s[58:59] nt
	v_add_u32_e32 v1, 0x1c00, v1
	global_load_dwordx4 v[228:231], v1, s[58:59] nt
	v_add_u32_e32 v1, 0x1c00, v1
	global_load_dwordx4 v[232:235], v1, s[58:59] nt
	v_add_u32_e32 v1, 0x1c00, v1
	s_cmp_lg_u32 s67, 0
	s_cselect_b64 vcc, -1, 0
	s_nop 1
	v_cndmask_b32_e32 v1, v1, v4, vcc
	global_load_dwordx4 v[236:239], v1, s[58:59] nt
	s_mul_i32 s63, s62, 0xc00
	s_add_u32 s63, s63, 0x15000800
	v_lshl_add_u32 v5, v0, 4, s63
	s_waitcnt vmcnt(18)
	s_cmp_eq_u32 s66, 0
	s_cbranch_scc1 .Lp2_nz_7
	v_mov_b32_e32 v8, 0
	v_mov_b32_e32 v9, 0
	v_mov_b32_e32 v10, 0
	v_mov_b32_e32 v11, 0

; __device__ __forceinline__ void unpack8(const u32x4 w, float (&f)[8]) { f[0] = bflo(w.x); f[1] = bfhi(w.x); f[2] = bflo(w.y); f[3] = bfhi(w.y); f[4] = bflo(w.z); f[5] = bfhi(w.z); f[6] = bflo(w.w); f[7] = bfhi(w.w); }
; __device__ __forceinline__ u32x4 pack8(const float (&f)[8]) { u32x4 o; o.x = pk2(f[0], f[1]); o.y = pk2(f[2], f[3]); o.z = pk2(f[4], f[5]); o.w = pk2(f[6], f[7]); return o; }
; template <int CH> __device__ __forceinline__ void p2_rwkv_chunk(const Params& p, int t0, int lane) {
;     ...
;     if (CH == 3 && chunk >= 232) {
;         if (chunk < 240) { const u32x4 zero = {0u, 0u, 0u, 0u};
; #pragma unroll 4
;             for (int i = 0; i < 16; ++i) *(u32x4*)(AP + (size_t)(t0 + i) * KLORA + 320 + (chunk - 232) * 8) = zero; }
;         return; }
;     const bf16_t* zc = (const bf16_t*)(ws + WS_Z) + (size_t)t0 * ZLD + c;
;     float mu[8], kq[8];
;     { const f32x4 m0 = *(const f32x4*)(p.in[8] + c), m1 = *(const f32x4*)(p.in[8] + c + 4);
; #pragma unroll
;       for (int i = 0; i < 4; ++i) { mu[i] = m0[i]; mu[4 + i] = m1[i]; } }
;     if (CH == 1) { const f32x4 q0 = *(const f32x4*)(p.in[14] + c - 512), q1 = *(const f32x4*)(p.in[14] + c - 512 + 4);
; #pragma unroll
;         for (int i = 0; i < 4; ++i) { kq[i] = q0[i]; kq[4 + i] = q1[i]; } }
;     float P[8], C[8], N[8];
;     if ((t0 & (T_SEQ - 1)) != 0) unpack8(__builtin_nontemporal_load((const u32x4*)(zc - ZLD)), P); else {
; #pragma unroll
;         for (int i = 0; i < 8; ++i) P[i] = 0.f; }
;     unpack8(__builtin_nontemporal_load((const u32x4*)(zc)), C);
;     u32x4 raw = __builtin_nontemporal_load((const u32x4*)(zc + ZLD));
;     ...
;         for (int q = 0; q < 8; ++q) zs[q] = C[q] + mu[q] * (0.5f * (P[q] + N[q]) - C[q]);
;         if (CH < 3) {
;             *(u32x4*)(RKV + (size_t)t * 1536 + c) = pack8(zs);
.Lp2_nz_8:
	v_lshlrev_b32_e32 v96, 16, v76
	v_and_b32_e32 v97, 0xffff0000, v76
	v_lshlrev_b32_e32 v98, 16, v77
	v_and_b32_e32 v99, 0xffff0000, v77
	v_lshlrev_b32_e32 v100, 16, v78
	v_and_b32_e32 v101, 0xffff0000, v78
	v_lshlrev_b32_e32 v102, 16, v79
	v_and_b32_e32 v103, 0xffff0000, v79
	v_add_f32_e32 v136, v80, v96
	v_add_f32_e32 v137, v81, v97
	v_add_f32_e32 v138, v82, v98
	v_add_f32_e32 v139, v83, v99
	v_add_f32_e32 v140, v84, v100
	v_add_f32_e32 v141, v85, v101
	v_add_f32_e32 v142, v86, v102
	v_add_f32_e32 v143, v87, v103
	v_fma_f32 v136, v136, 0.5, -v88
	v_fma_f32 v137, v137, 0.5, -v89
	v_fma_f32 v138, v138, 0.5, -v90
	v_fma_f32 v139, v139, 0.5, -v91
	v_fma_f32 v140, v140, 0.5, -v92
	v_fma_f32 v141, v141, 0.5, -v93
	v_fma_f32 v142, v142, 0.5, -v94
	v_fma_f32 v143, v143, 0.5, -v95
	v_fma_f32 v128, v104, v136, v88
	v_fma_f32 v129, v105, v137, v89
	v_fma_f32 v130, v106, v138, v90
	v_fma_f32 v131, v107, v139, v91
	v_fma_f32 v132, v108, v140, v92
	v_fma_f32 v133, v109, v141, v93
	v_fma_f32 v134, v110, v142, v94
	v_fma_f32 v135, v111, v143, v95
	v_cvt_pk_bf16_f32 v246, v128, v129
	v_cvt_pk_bf16_f32 v247, v130, v131
	v_cvt_pk_bf16_f32 v248, v132, v133
	v_cvt_pk_bf16_f32 v249, v134, v135
	global_store_dwordx4 v5, v[246:249], s[58:59]
	v_add_u32_e32 v5, 0xc00, v5
	s_mov_b32 s98, 0x1800
	s_mov_b32 s99, 0
	v_lshl_add_u64 v[2:3], v[250:251], 0, s[98:99]
	v_mov_b32_e32 v104, 0
	v_mov_b32_e32 v105, 0
	v_mov_b32_e32 v106, 0
	v_mov_b32_e32 v107, 0
	v_mov_b32_e32 v108, 0
	v_mov_b32_e32 v109, 0
	v_mov_b32_e32 v110, 0
	v_mov_b32_e32 v111, 0
	v_cmp_gt_u32_e64 s[64:65], 40, v0
	s_mov_b64 s[42:43], exec
	s_nop 0
	s_and_b64 exec, exec, s[64:65]
	global_load_dwordx4 v[104:107], v[2:3], off
	global_load_dwordx4 v[108:111], v[2:3], off offset:16
	s_mov_b64 exec, s[42:43]
	s_mul_i32 s63, s62, 0x1c00
	s_add_u32 s63, s63, 0x7000e80
	v_lshl_add_u32 v4, v0, 4, s63
	v_add_u32_e32 v1, 0xffffe400, v4
	s_cmp_lg_u32 s66, 0
	s_cselect_b64 vcc, -1, 0
	s_nop 1
	v_cndmask_b32_e32 v1, v1, v4, vcc
	global_load_dwordx4 v[8:11], v1, s[58:59] nt
	global_load_dwordx4 v[12:15], v4, s[58:59] nt
	v_mov_b32_e32 v1, v4
	v_add_u32_e32 v1, 0x1c00, v1
	global_load_dwordx4 v[16:19], v1, s[58:59] nt
	v_add_u32_e32 v1, 0x1c00, v1
	global_load_dwordx4 v[20:23], v1, s[58:59] nt
	v_add_u32_e32 v1, 0x1c00, v1
	global_load_dwordx4 v[24:27], v1, s[58:59] nt
	v_add_u32_e32 v1, 0x1c00, v1
	global_load_dwordx4 v[28:31], v1, s[58:59] nt
	v_add_u32_e32 v1, 0x1c00, v1
	global_load_dwordx4 v[32:35], v1, s[58:59] nt
	v_add_u32_e32 v1, 0x1c00, v1
	global_load_dwordx4 v[36:39], v1, s[58:59] nt
	v_add_u32_e32 v1, 0x1c00, v1
	global_load_dwordx4 v[40:43], v1, s[58:59] nt
	v_add_u32_e32 v1, 0x1c00, v1
	global_load_dwordx4 v[44:47], v1, s[58:59] nt
	v_add_u32_e32 v1, 0x1c00, v1
	global_load_dwordx4 v[48:51], v1, s[58:59] nt
	v_add_u32_e32 v1, 0x1c00, v1
	global_load_dwordx4 v[52:55], v1, s[58:59] nt
	v_add_u32_e32 v1, 0x1c00, v1
	global_load_dwordx4 v[56:59], v1, s[58:59] nt
	v_add_u32_e32 v1, 0x1c00, v1
	global_load_dwordx4 v[60:63], v1, s[58:59] nt
	v_add_u32_e32 v1, 0x1c00, v1
	global_load_dwordx4 v[64:67], v1, s[58:59] nt
	v_add_u32_e32 v1, 0x1c00, v1
	global_load_dwordx4 v[68:71], v1, s[58:59] nt
	v_add_u32_e32 v1, 0x1c00, v1
	global_load_dwordx4 v[72:75], v1, s[58:59] nt
	v_add_u32_e32 v1, 0x1c00, v1
	s_cmp_lg_u32 s67, 0
	s_cselect_b64 vcc, -1, 0
	s_nop 1
	v_cndmask_b32_e32 v1, v1, v4, vcc
	global_load_dwordx4 v[76:79], v1, s[58:59] nt
	v_cmp_gt_u32_e64 s[64:65], 40, v0
	v_cmp_gt_u32_e64 s[74:75], 16, v0
	v_cmp_gt_u32_e64 s[76:77], 24, v0
	v_cmp_gt_u32_e64 s[36:37], 48, v0
	s_mul_i32 s63, s62, 0x300
	v_lshl_add_u32 v5, v0, 4, s63
	s_waitcnt vmcnt(18)
	s_cmp_eq_u32 s66, 0
	s_cbranch_scc1 .Lp2_nz_9
	v_mov_b32_e32 v168, 0
	v_mov_b32_e32 v169, 0
	v_mov_b32_e32 v170, 0
	v_mov_b32_e32 v171, 0
